# speedup vs baseline: 1.0246x; 1.0246x over previous
; DI float bf_lo(unsigned u) { return __uint_as_float(u << 16); }
; DI float bf_hi(unsigned u) { return __uint_as_float(u & 0xffff0000u); }
; DI int obid() { int b = blockIdx.x; asm volatile("" : "+s"(b)); return b; }
; DI f32x4 h4_to_f4(u32x2 t) { const h16x4 h = __builtin_bit_cast(h16x4, t); return (f32x4){(float)h[0], (float)h[1], (float)h[2], (float)h[3]}; }
; DI void phase_row(const Params& P, const void* xs, int sh, void* xd, int dh, int ln, int gl, int gidx, float wgt, int modl, int shidx, bool dry = false) {
;     ...
;     for (int row = obid() * 8 + w; row < T; row += gridDim.x * 8) {
;         const int b = row >= SEQ;
;         f32x4 v[4];
; #pragma unroll
;         for (int j = 0; j < 4; ++j) { const size_t e = (size_t)row * D + 4 * lane + 256 * j;
;             if (sh) v[j] = h4_to_f4(__builtin_nontemporal_load((const u32x2*)((const unsigned short*)xs + e))); else v[j] = __builtin_nontemporal_load((const f32x4*)((const float*)xs + e)); }
;         if (ln >= 0) {
;             u32x2 fv[4];
; #pragma unroll
;             for (int j = 0; j < 4; ++j) fv[j] = __builtin_nontemporal_load((const u32x2*)(U + (size_t)row * D + 4 * lane + 256 * j));
;             const float* gate = mod + (gl * 2 + b) * 9216 + gidx * 1024;
; #pragma unroll
;             for (int j = 0; j < 4; ++j) { const f32x4 g = (*(const f32x4*)(gate + 4 * lane + 256 * j) + 1.f) * wgt;
;                 const f32x4 f = {bf_lo(fv[j].x), bf_hi(fv[j].x), bf_lo(fv[j].y), bf_hi(fv[j].y)};
;                 v[j] = v[j] * DN_ALPHA + g * f; }
.LBB0_7:
	v_readlane_b32 s84, v246, 0
	v_readlane_b32 s85, v246, 1
	s_load_dwordx16 s[4:19], s[84:85], 0x0
	v_writelane_b32 v245, s68, 33
	s_mov_b64 s[2:3], -1
	s_mov_b64 s[60:61], 0
	s_mov_b64 s[48:49], 0
	s_waitcnt lgkmcnt(0)
	v_writelane_b32 v245, s4, 34
	s_nop 1
	v_writelane_b32 v245, s5, 35
	v_writelane_b32 v245, s6, 36
	v_writelane_b32 v245, s7, 37
	v_writelane_b32 v245, s8, 38
	v_writelane_b32 v245, s9, 39
	v_writelane_b32 v245, s10, 40
	v_writelane_b32 v245, s11, 41
	v_writelane_b32 v245, s12, 42
	v_writelane_b32 v245, s13, 43
	v_writelane_b32 v245, s14, 44
	v_writelane_b32 v245, s15, 45
	v_writelane_b32 v245, s16, 46
	v_writelane_b32 v245, s17, 47
	v_writelane_b32 v245, s18, 48
	v_writelane_b32 v245, s19, 49
	s_load_dwordx16 s[4:19], s[84:85], 0x40
	s_load_dwordx8 s[40:47], s[84:85], 0xc8
	s_waitcnt lgkmcnt(0)
	v_writelane_b32 v245, s40, 50
	s_nop 1
	v_writelane_b32 v245, s41, 51
	v_writelane_b32 v245, s42, 52
	v_writelane_b32 v245, s43, 53
	v_writelane_b32 v245, s44, 54
	v_writelane_b32 v245, s45, 55
	v_writelane_b32 v245, s46, 56
	v_writelane_b32 v245, s47, 57
	s_nop 0
	v_readlane_b32 s26, v245, 33
	s_cmp_lt_i32 s26, 11
	s_cbranch_scc1 .LBB0_117
	v_readlane_b32 s2, v245, 33
	s_cmp_gt_i32 s2, 21
	s_cbranch_scc0 .LBB0_17
	s_cmp_gt_i32 s2, 24
	s_cbranch_scc0 .LBB0_18
	s_cmp_gt_i32 s2, 27
	s_cbranch_scc0 .LBB0_19
	s_cmp_eq_u32 s2, 28
	s_mov_b64 s[48:49], -1
	s_cbranch_scc0 .LBB0_16
	s_load_dwordx8 s[56:63], s[84:85], 0xc8
	s_waitcnt vmcnt(0)
	v_mov_b32_e32 v0, v195
	s_mov_b32 s2, s28
	s_waitcnt lgkmcnt(0)
	s_mov_b64 s[30:31], s[62:63]
	s_mov_b64 s[26:27], s[62:63]
	v_ashrrev_i32_e32 v1, 6, v0
	s_mov_b64 s[40:41], s[62:63]
	s_nop 0
	v_lshl_add_u32 v32, s2, 3, v1
	v_cmp_gt_i32_e32 vcc, s75, v32
	s_and_saveexec_b64 s[2:3], vcc
	s_mov_b32 s42, 0x3fb504f3
	s_cbranch_execz .LBB0_15
	v_lshlrev_b32_e32 v0, 2, v0
	s_load_dwordx16 s[44:59], s[84:85], 0x0
	v_and_b32_e32 v34, 0xfc, v0
	v_lshlrev_b32_e32 v184, 1, v34
	v_lshl_add_u64 v[0:1], s[40:41], 0, v[184:185]
	s_mov_b64 s[36:37], 0x5808000
	v_lshlrev_b32_e32 v184, 2, v34
	v_lshl_add_u64 v[36:37], v[0:1], 0, s[36:37]
	v_lshl_add_u64 v[0:1], s[26:27], 0, v[184:185]
	s_mov_b64 s[26:27], 0x5588000
	v_lshl_add_u64 v[38:39], v[0:1], 0, s[26:27]
	s_waitcnt lgkmcnt(0)
	v_lshl_add_u64 v[0:1], s[58:59], 0, v[184:185]
	s_mov_b64 s[26:27], 0x5000
	s_add_u32 s30, s30, 0x16008000
	v_lshl_add_u64 v[40:41], v[0:1], 0, s[26:27]
	v_lshl_add_u64 v[0:1], s[4:5], 0, v[184:185]
	s_addc_u32 s31, s31, 0
	v_lshl_add_u64 v[42:43], v[0:1], 0, s[26:27]
	s_mov_b64 s[40:41], 0
	global_load_dwordx4 v[108:111], v[40:41], off
	global_load_dwordx4 v[100:103], v[40:41], off offset:1024
	global_load_dwordx4 v[124:127], v[42:43], off
	global_load_dwordx4 v[116:119], v[42:43], off offset:1024
	global_load_dwordx4 v[112:115], v[40:41], off offset:2048
	global_load_dwordx4 v[104:107], v[40:41], off offset:3072
	global_load_dwordx4 v[128:131], v[42:43], off offset:2048
	global_load_dwordx4 v[120:123], v[42:43], off offset:3072
	v_mov_b32_e32 v184, v196
	v_lshl_add_u64 v[164:165], v[38:39], 0, v[184:185]
	flat_load_dwordx4 v[132:135], v[164:165]
	flat_load_dwordx4 v[136:139], v[164:165] offset:1024
	flat_load_dwordx4 v[140:143], v[164:165] offset:2048
	flat_load_dwordx4 v[144:147], v[164:165] offset:3072
	v_mov_b32_e32 v184, v197
	v_lshl_add_u64 v[164:165], v[38:39], 0, v[184:185]
	flat_load_dwordx4 v[148:151], v[164:165]
	flat_load_dwordx4 v[152:155], v[164:165] offset:1024
	flat_load_dwordx4 v[156:159], v[164:165] offset:2048
	flat_load_dwordx4 v[160:163], v[164:165] offset:3072
	s_waitcnt vmcnt(0) lgkmcnt(0)
.LBB0_14:
	v_cmp_lt_i32_e32 vcc, s23, v32
	v_ashrrev_i32_e32 v33, 31, v32
	v_lshlrev_b64 v[62:63], 10, v[32:33]
	v_cndmask_b32_e32 v184, v196, v197, vcc
	v_lshl_add_u64 v[56:57], v[38:39], 0, v[184:185]
	v_lshlrev_b64 v[60:61], 11, v[32:33]
	v_or_b32_e32 v62, v62, v34
	v_cndmask_b32_e32 v44, v132, v148, vcc
	v_cndmask_b32_e32 v45, v133, v149, vcc
	v_cndmask_b32_e32 v46, v134, v150, vcc
	v_cndmask_b32_e32 v47, v135, v151, vcc
	v_cndmask_b32_e32 v48, v136, v152, vcc
	v_cndmask_b32_e32 v49, v137, v153, vcc
	v_cndmask_b32_e32 v50, v138, v154, vcc
	v_cndmask_b32_e32 v51, v139, v155, vcc
	v_cndmask_b32_e32 v52, v140, v156, vcc
	v_cndmask_b32_e32 v53, v141, v157, vcc
	v_cndmask_b32_e32 v54, v142, v158, vcc
	v_cndmask_b32_e32 v55, v143, v159, vcc
	v_cndmask_b32_e32 v56, v144, v160, vcc
	v_cndmask_b32_e32 v57, v145, v161, vcc
	v_cndmask_b32_e32 v58, v146, v162, vcc
	v_cndmask_b32_e32 v59, v147, v163, vcc
	s_nop 0
	v_lshl_add_u64 v[60:61], v[36:37], 0, v[60:61]
	v_lshlrev_b64 v[70:71], 1, v[62:63]
	flat_load_dwordx2 v[64:65], v[60:61] nt
	flat_load_dwordx2 v[66:67], v[60:61] offset:512 nt
	flat_load_dwordx2 v[68:69], v[60:61] offset:1024 nt
	s_nop 0
	flat_load_dwordx2 v[60:61], v[60:61] offset:1536 nt
	v_lshl_add_u64 v[72:73], s[30:31], 0, v[70:71]
	flat_load_dwordx2 v[72:73], v[72:73] nt
	v_or_b32_e32 v74, 0x200, v70
	v_mov_b32_e32 v75, v71
	v_or_b32_e32 v76, 0x400, v70
	v_mov_b32_e32 v77, v71
	v_or_b32_e32 v70, 0x600, v70
	v_lshl_add_u64 v[74:75], s[30:31], 0, v[74:75]
	v_lshl_add_u64 v[76:77], s[30:31], 0, v[76:77]
	v_lshl_add_u64 v[70:71], s[30:31], 0, v[70:71]
	flat_load_dwordx2 v[74:75], v[74:75] nt
	s_nop 0
	flat_load_dwordx2 v[76:77], v[76:77] nt
	s_nop 0
	flat_load_dwordx2 v[70:71], v[70:71] nt
	v_add_u32_e32 v32, s70, v32
	v_cmp_lt_i32_e32 vcc, s20, v32
	s_or_b64 s[40:41], vcc, s[40:41]
	v_lshl_add_u64 v[62:63], v[62:63], 2, s[60:61]
	s_waitcnt vmcnt(0) lgkmcnt(0)
; DI float bf_lo(unsigned u) { return __uint_as_float(u << 16); }
; DI float bf_hi(unsigned u) { return __uint_as_float(u & 0xffff0000u); }
; DI void phase_row(const Params& P, const void* xs, int sh, void* xd, int dh, int ln, int gl, int gidx, float wgt, int modl, int shidx, bool dry = false) {
;     ...
;             const float* gate = mod + (gl * 2 + b) * 9216 + gidx * 1024;
; #pragma unroll
;             for (int j = 0; j < 4; ++j) { const f32x4 g = (*(const f32x4*)(gate + 4 * lane + 256 * j) + 1.f) * wgt;
;                 const f32x4 f = {bf_lo(fv[j].x), bf_hi(fv[j].x), bf_lo(fv[j].y), bf_hi(fv[j].y)};
;                 v[j] = v[j] * DN_ALPHA + g * f; }
;             float s = 0.f;
; #pragma unroll
;             for (int j = 0; j < 4; ++j) s += (v[j][0] + v[j][1]) + (v[j][2] + v[j][3]);
	v_pk_add_f32 v[46:47], v[46:47], 1.0 op_sel_hi:[1,0]
	v_pk_add_f32 v[50:51], v[50:51], 1.0 op_sel_hi:[1,0]
	v_pk_add_f32 v[54:55], v[54:55], 1.0 op_sel_hi:[1,0]
	v_pk_add_f32 v[58:59], v[58:59], 1.0 op_sel_hi:[1,0]
	v_lshlrev_b32_e32 v78, 16, v64
	v_and_b32_e32 v79, 0xffff0000, v64
	v_lshlrev_b32_e32 v64, 16, v65
	v_and_b32_e32 v65, 0xffff0000, v65
	v_lshlrev_b32_e32 v84, 16, v60
	v_and_b32_e32 v85, 0xffff0000, v60
	v_lshlrev_b32_e32 v60, 16, v61
	v_and_b32_e32 v61, 0xffff0000, v61
	v_pk_mul_f32 v[46:47], v[46:47], 0.5 op_sel_hi:[1,0]
	v_pk_mul_f32 v[58:59], v[58:59], 0.5 op_sel_hi:[1,0]
	v_lshlrev_b32_e32 v80, 16, v66
	v_and_b32_e32 v81, 0xffff0000, v66
	v_lshlrev_b32_e32 v66, 16, v67
	v_and_b32_e32 v67, 0xffff0000, v67
	v_lshlrev_b32_e32 v82, 16, v68
	v_and_b32_e32 v83, 0xffff0000, v68
	v_lshlrev_b32_e32 v68, 16, v69
	v_and_b32_e32 v69, 0xffff0000, v69
	v_pk_mul_f32 v[50:51], v[50:51], 0.5 op_sel_hi:[1,0]
	v_pk_mul_f32 v[54:55], v[54:55], 0.5 op_sel_hi:[1,0]
	v_pk_mul_f32 v[46:47], v[46:47], v[64:65]
	v_pk_mul_f32 v[58:59], v[58:59], v[60:61]
	v_cvt_f32_f16_e32 v60, v72
	v_cvt_f32_f16_sdwa v61, v72 dst_sel:DWORD dst_unused:UNUSED_PAD src0_sel:WORD_1
	v_cvt_f32_f16_e32 v64, v73
	v_cvt_f32_f16_sdwa v65, v73 dst_sel:DWORD dst_unused:UNUSED_PAD src0_sel:WORD_1
	v_pk_add_f32 v[44:45], v[44:45], 1.0 op_sel_hi:[1,0]
	v_pk_mul_f32 v[50:51], v[50:51], v[66:67]
	v_pk_mul_f32 v[54:55], v[54:55], v[68:69]
	v_cvt_f32_f16_e32 v66, v74
	v_cvt_f32_f16_sdwa v67, v74 dst_sel:DWORD dst_unused:UNUSED_PAD src0_sel:WORD_1
	v_cvt_f32_f16_e32 v68, v75
	v_cvt_f32_f16_sdwa v69, v75 dst_sel:DWORD dst_unused:UNUSED_PAD src0_sel:WORD_1
	v_pk_add_f32 v[48:49], v[48:49], 1.0 op_sel_hi:[1,0]
	v_pk_mul_f32 v[44:45], v[44:45], 0.5 op_sel_hi:[1,0]
	v_cvt_f32_f16_e32 v72, v76
	v_cvt_f32_f16_sdwa v73, v76 dst_sel:DWORD dst_unused:UNUSED_PAD src0_sel:WORD_1
	v_cvt_f32_f16_e32 v74, v77
	v_cvt_f32_f16_sdwa v75, v77 dst_sel:DWORD dst_unused:UNUSED_PAD src0_sel:WORD_1
	v_pk_add_f32 v[52:53], v[52:53], 1.0 op_sel_hi:[1,0]
	v_pk_mul_f32 v[48:49], v[48:49], 0.5 op_sel_hi:[1,0]
	v_pk_mul_f32 v[44:45], v[44:45], v[78:79]
	v_cvt_f32_f16_e32 v76, v70
	v_cvt_f32_f16_sdwa v77, v70 dst_sel:DWORD dst_unused:UNUSED_PAD src0_sel:WORD_1
	v_cvt_f32_f16_e32 v70, v71
	v_cvt_f32_f16_sdwa v71, v71 dst_sel:DWORD dst_unused:UNUSED_PAD src0_sel:WORD_1
	v_pk_add_f32 v[56:57], v[56:57], 1.0 op_sel_hi:[1,0]
	v_pk_mul_f32 v[52:53], v[52:53], 0.5 op_sel_hi:[1,0]
	v_pk_mul_f32 v[48:49], v[48:49], v[80:81]
	v_pk_fma_f32 v[46:47], v[64:65], s[42:43], v[46:47] op_sel_hi:[1,0,1]
	v_pk_fma_f32 v[44:45], v[60:61], s[42:43], v[44:45] op_sel_hi:[1,0,1]
	v_pk_mul_f32 v[56:57], v[56:57], 0.5 op_sel_hi:[1,0]
	v_pk_mul_f32 v[52:53], v[52:53], v[82:83]
	v_pk_fma_f32 v[50:51], v[68:69], s[42:43], v[50:51] op_sel_hi:[1,0,1]
	v_pk_fma_f32 v[48:49], v[66:67], s[42:43], v[48:49] op_sel_hi:[1,0,1]
	v_add_f32_e32 v33, v44, v45
	v_add_f32_e32 v35, v46, v47
	v_pk_mul_f32 v[56:57], v[56:57], v[84:85]
	v_pk_fma_f32 v[54:55], v[74:75], s[42:43], v[54:55] op_sel_hi:[1,0,1]
	v_pk_fma_f32 v[52:53], v[72:73], s[42:43], v[52:53] op_sel_hi:[1,0,1]
	v_add_f32_e32 v33, v33, v35
	v_add_f32_e32 v35, v48, v49
	v_add_f32_e32 v60, v50, v51
	v_pk_fma_f32 v[58:59], v[70:71], s[42:43], v[58:59] op_sel_hi:[1,0,1]
	v_pk_fma_f32 v[56:57], v[76:77], s[42:43], v[56:57] op_sel_hi:[1,0,1]
	v_add_f32_e32 v61, v52, v53
	v_add_f32_e32 v64, v54, v55
	v_add_f32_e32 v33, 0, v33
	v_add_f32_e32 v35, v35, v60
	v_add_f32_e32 v65, v56, v57
	v_add_f32_e32 v66, v58, v59
	v_add_f32_e32 v60, v61, v64
	v_add_f32_e32 v33, v33, v35
	v_add_f32_e32 v61, v65, v66
	v_add_f32_e32 v33, v33, v60
	v_add_f32_e32 v33, v33, v61
	s_nop 1
	v_add_f32_dpp v33, v33, v33 quad_perm:[1,0,3,2] row_mask:0xf bank_mask:0xf bound_ctrl:1
	s_nop 1
; DI void phase_row(const Params& P, const void* xs, int sh, void* xd, int dh, int ln, int gl, int gidx, float wgt, int modl, int shidx, bool dry = false) {
;     ...
;             const float mean = wave_sum(s, lane) * (1.f / 1024.f);
;             float q = 0.f;
; #pragma unroll
;             for (int j = 0; j < 4; ++j) { v[j] = v[j] - mean; q += (v[j][0] * v[j][0] + v[j][1] * v[j][1]) + (v[j][2] * v[j][2] + v[j][3] * v[j][3]); }
;             const float rstd = rsqrtf(wave_sum(q, lane) * (1.f / 1024.f) + LN_EPS);
; #pragma unroll
;             for (int j = 0; j < 4; ++j) { const f32x4 g = *(const f32x4*)(P.ln_g + ln * D + 4 * lane + 256 * j), bb = *(const f32x4*)(P.ln_b + ln * D + 4 * lane + 256 * j); v[j] = v[j] * rstd * g + bb; }
;             if (dry) { if (v[0][0] + v[1][1] + v[2][2] + v[3][3] == 12345.678f) P.xbuf[row] = 0.f; continue; }
; #pragma unroll
;             for (int j = 0; j < 4; ++j) { const size_t e = (size_t)row * D + 4 * lane + 256 * j;
;                 if (dh) __builtin_nontemporal_store(f4_to_h4(v[j]), (u32x2*)((unsigned short*)xd + e)); else __builtin_nontemporal_store(v[j], (f32x4*)((float*)xd + e)); }
	v_add_f32_dpp v33, v33, v33 quad_perm:[2,3,0,1] row_mask:0xf bank_mask:0xf bound_ctrl:1
	s_nop 1
	v_add_f32_dpp v33, v33, v33 row_half_mirror row_mask:0xf bank_mask:0xf bound_ctrl:1
	s_nop 1
	v_add_f32_dpp v33, v33, v33 row_mirror row_mask:0xf bank_mask:0xf bound_ctrl:1
	v_mov_b32_e32 v35, v33
	s_nop 1
	v_permlane16_swap_b32_e32 v33, v35
	v_add_f32_e32 v33, v33, v35
	v_mov_b32_e32 v35, v33
	s_nop 1
	v_permlane32_swap_b32_e32 v33, v35
	v_add_f32_e32 v33, v33, v35
	v_fmac_f32_e32 v47, 0xba800000, v33
	v_fmac_f32_e32 v45, 0xba800000, v33
	v_fmac_f32_e32 v51, 0xba800000, v33
	v_fmac_f32_e32 v49, 0xba800000, v33
	v_fmamk_f32 v46, v33, 0xba800000, v46
	v_fmamk_f32 v44, v33, 0xba800000, v44
	v_fmamk_f32 v50, v33, 0xba800000, v50
	v_fmamk_f32 v48, v33, 0xba800000, v48
	v_fmamk_f32 v54, v33, 0xba800000, v54
	v_fmac_f32_e32 v55, 0xba800000, v33
	v_fmamk_f32 v52, v33, 0xba800000, v52
	v_fmac_f32_e32 v53, 0xba800000, v33
	v_fmamk_f32 v58, v33, 0xba800000, v58
	v_fmac_f32_e32 v59, 0xba800000, v33
	v_fmamk_f32 v56, v33, 0xba800000, v56
	v_fmac_f32_e32 v57, 0xba800000, v33
	v_mul_f32_e32 v33, v45, v45
	v_mul_f32_e32 v35, v47, v47
	v_mul_f32_e32 v60, v49, v49
	v_mul_f32_e32 v61, v51, v51
	v_mul_f32_e32 v64, v53, v53
	v_mul_f32_e32 v65, v55, v55
	v_fmac_f32_e32 v33, v44, v44
	v_fmac_f32_e32 v35, v46, v46
	v_fmac_f32_e32 v60, v48, v48
	v_fmac_f32_e32 v61, v50, v50
	v_mul_f32_e32 v66, v57, v57
	v_mul_f32_e32 v67, v59, v59
	v_fmac_f32_e32 v64, v52, v52
	v_fmac_f32_e32 v65, v54, v54
	v_add_f32_e32 v33, v33, v35
	v_add_f32_e32 v35, v60, v61
	v_fmac_f32_e32 v66, v56, v56
	v_fmac_f32_e32 v67, v58, v58
	v_add_f32_e32 v60, v64, v65
	v_add_f32_e32 v33, v33, v35
	v_add_f32_e32 v61, v66, v67
	v_add_f32_e32 v33, v60, v33
	v_add_f32_e32 v33, v61, v33
	s_nop 1
	v_add_f32_dpp v33, v33, v33 quad_perm:[1,0,3,2] row_mask:0xf bank_mask:0xf bound_ctrl:1
	s_nop 1
	v_add_f32_dpp v33, v33, v33 quad_perm:[2,3,0,1] row_mask:0xf bank_mask:0xf bound_ctrl:1
	s_nop 1
	v_add_f32_dpp v33, v33, v33 row_half_mirror row_mask:0xf bank_mask:0xf bound_ctrl:1
	s_nop 1
	v_add_f32_dpp v33, v33, v33 row_mirror row_mask:0xf bank_mask:0xf bound_ctrl:1
	v_mov_b32_e32 v35, v33
	s_nop 1
	v_permlane16_swap_b32_e32 v33, v35
	v_add_f32_e32 v33, v33, v35
	v_mov_b32_e32 v35, v33
	s_nop 1
	v_permlane32_swap_b32_e32 v33, v35
	v_add_f32_e32 v33, v33, v35
	v_fmamk_f32 v33, v33, 0x3a800000, v198
	v_mul_f32_e32 v35, 0x4b800000, v33
	v_cmp_gt_f32_e32 vcc, s25, v33
	s_nop 1
	v_cndmask_b32_e32 v33, v33, v35, vcc
	v_rsq_f32_e32 v33, v33
	s_nop 0
	v_mul_f32_e32 v35, 0x45800000, v33
	v_cndmask_b32_e32 v60, v33, v35, vcc
	v_pk_mul_f32 v[44:45], v[44:45], v[60:61] op_sel_hi:[1,0]
	v_pk_mul_f32 v[46:47], v[46:47], v[60:61] op_sel_hi:[1,0]
	v_pk_mul_f32 v[48:49], v[48:49], v[60:61] op_sel_hi:[1,0]
	v_pk_mul_f32 v[50:51], v[50:51], v[60:61] op_sel_hi:[1,0]
	v_pk_mul_f32 v[52:53], v[52:53], v[60:61] op_sel_hi:[1,0]
	v_pk_mul_f32 v[54:55], v[54:55], v[60:61] op_sel_hi:[1,0]
	v_pk_mul_f32 v[56:57], v[56:57], v[60:61] op_sel_hi:[1,0]
	v_pk_mul_f32 v[58:59], v[58:59], v[60:61] op_sel_hi:[1,0]
	v_pk_fma_f32 v[10:11], v[110:111], v[46:47], v[126:127]
	v_pk_fma_f32 v[8:9], v[108:109], v[44:45], v[124:125]
	v_pk_fma_f32 v[2:3], v[102:103], v[50:51], v[118:119]
	v_pk_fma_f32 v[0:1], v[100:101], v[48:49], v[116:117]
	v_pk_fma_f32 v[14:15], v[114:115], v[54:55], v[130:131]
	v_pk_fma_f32 v[12:13], v[112:113], v[52:53], v[128:129]
	v_pk_fma_f32 v[6:7], v[106:107], v[58:59], v[122:123]
	v_pk_fma_f32 v[4:5], v[104:105], v[56:57], v[120:121]
	global_store_dwordx4 v[62:63], v[8:11], off nt
	global_store_dwordx4 v[62:63], v[0:3], off offset:1024 nt
	global_store_dwordx4 v[62:63], v[12:15], off offset:2048 nt
	global_store_dwordx4 v[62:63], v[4:7], off offset:3072 nt
	s_andn2_b64 exec, exec, s[40:41]
	s_cbranch_execnz .LBB0_14

; DI float bf_lo(unsigned u) { return __uint_as_float(u << 16); }
; DI float bf_hi(unsigned u) { return __uint_as_float(u & 0xffff0000u); }
; DI int obid() { int b = blockIdx.x; asm volatile("" : "+s"(b)); return b; }
; DI f32x4 h4_to_f4(u32x2 t) { const h16x4 h = __builtin_bit_cast(h16x4, t); return (f32x4){(float)h[0], (float)h[1], (float)h[2], (float)h[3]}; }
; DI void phase_row(const Params& P, const void* xs, int sh, void* xd, int dh, int ln, int gl, int gidx, float wgt, int modl, int shidx, bool dry = false) {
;     ...
;     for (int row = obid() * 8 + w; row < T; row += gridDim.x * 8) {
;         const int b = row >= SEQ;
;         f32x4 v[4];
; #pragma unroll
;         for (int j = 0; j < 4; ++j) { const size_t e = (size_t)row * D + 4 * lane + 256 * j;
;             if (sh) v[j] = h4_to_f4(__builtin_nontemporal_load((const u32x2*)((const unsigned short*)xs + e))); else v[j] = __builtin_nontemporal_load((const f32x4*)((const float*)xs + e)); }
;         if (ln >= 0) {
;             u32x2 fv[4];
; #pragma unroll
;             for (int j = 0; j < 4; ++j) fv[j] = __builtin_nontemporal_load((const u32x2*)(U + (size_t)row * D + 4 * lane + 256 * j));
;             const float* gate = mod + (gl * 2 + b) * 9216 + gidx * 1024;
; #pragma unroll
;             for (int j = 0; j < 4; ++j) { const f32x4 g = (*(const f32x4*)(gate + 4 * lane + 256 * j) + 1.f) * wgt;
;                 const f32x4 f = {bf_lo(fv[j].x), bf_hi(fv[j].x), bf_lo(fv[j].y), bf_hi(fv[j].y)};
;                 v[j] = v[j] * DN_ALPHA + g * f; }
.LBB0_19:
	s_cbranch_execz .LBB0_25
	v_readlane_b32 s2, v245, 33
	s_cmp_eq_u32 s2, 25
	s_mov_b64 s[48:49], -1
	s_cbranch_scc0 .LBB0_25
	s_load_dwordx8 s[60:67], s[84:85], 0xc8
	s_waitcnt vmcnt(0)
	v_mov_b32_e32 v0, v195
	s_mov_b32 s2, s28
	s_waitcnt lgkmcnt(0)
	s_mov_b64 s[30:31], s[66:67]
	s_mov_b64 s[26:27], s[66:67]
	v_ashrrev_i32_e32 v1, 6, v0
	s_mov_b64 s[40:41], s[66:67]
	s_nop 0
	v_lshl_add_u32 v48, s2, 3, v1
	v_cmp_gt_i32_e32 vcc, s75, v48
	s_and_saveexec_b64 s[2:3], vcc
	s_mov_b32 s42, 0x3fb504f3
	s_mov_b64 s[46:47], 0x1000
	s_cbranch_execz .LBB0_24
	v_lshlrev_b32_e32 v0, 2, v0
	s_load_dwordx16 s[48:63], s[84:85], 0x0
	v_and_b32_e32 v50, 0xfc, v0
	s_add_u32 s30, s30, 0x16008000
	v_lshlrev_b32_e32 v184, 1, v50
	s_addc_u32 s31, s31, 0
	v_lshl_add_u64 v[0:1], s[40:41], 0, v[184:185]
	s_mov_b64 s[36:37], 0x5808000
	v_lshlrev_b32_e32 v184, 2, v50
	v_lshl_add_u64 v[52:53], v[0:1], 0, s[36:37]
	v_lshl_add_u64 v[0:1], s[26:27], 0, v[184:185]
	s_mov_b64 s[36:37], 0x5585000
	s_add_u32 s40, s26, 0x5586000
	v_lshl_add_u64 v[54:55], v[0:1], 0, s[36:37]
	s_addc_u32 s41, s27, 0
	s_waitcnt lgkmcnt(0)
	v_lshl_add_u64 v[0:1], s[62:63], 0, v[184:185]
	s_mov_b64 s[26:27], 0x4000
	v_lshl_add_u64 v[56:57], v[0:1], 0, s[26:27]
	v_lshl_add_u64 v[0:1], s[4:5], 0, v[184:185]
	v_lshl_add_u64 v[58:59], v[0:1], 0, s[26:27]
	s_mov_b64 s[44:45], 0
	global_load_dwordx4 v[116:119], v[56:57], off
	global_load_dwordx4 v[108:111], v[56:57], off offset:1024
	global_load_dwordx4 v[132:135], v[58:59], off
	global_load_dwordx4 v[124:127], v[58:59], off offset:1024
	global_load_dwordx4 v[120:123], v[56:57], off offset:2048
	global_load_dwordx4 v[112:115], v[56:57], off offset:3072
	global_load_dwordx4 v[136:139], v[58:59], off offset:2048
	global_load_dwordx4 v[128:131], v[58:59], off offset:3072
	v_mov_b32_e32 v184, v196
	v_lshl_add_u64 v[106:107], v[54:55], 0, v[184:185]
	flat_load_dwordx4 v[140:143], v[106:107]
	flat_load_dwordx4 v[144:147], v[106:107] offset:1024
	flat_load_dwordx4 v[148:151], v[106:107] offset:2048
	flat_load_dwordx4 v[152:155], v[106:107] offset:3072
	v_mov_b32_e32 v184, v197
	v_lshl_add_u64 v[106:107], v[54:55], 0, v[184:185]
	flat_load_dwordx4 v[156:159], v[106:107]
	flat_load_dwordx4 v[160:163], v[106:107] offset:1024
	flat_load_dwordx4 v[164:167], v[106:107] offset:2048
	flat_load_dwordx4 v[168:171], v[106:107] offset:3072
	s_waitcnt vmcnt(0) lgkmcnt(0)
.LBB0_23:
	v_ashrrev_i32_e32 v49, 31, v48
	v_cmp_lt_i32_e32 vcc, s23, v48
	v_lshlrev_b64 v[72:73], 11, v[48:49]
	v_lshl_or_b32 v88, v50, 1, v72
	v_cndmask_b32_e32 v184, v196, v197, vcc
	v_mov_b32_e32 v89, v73
	v_lshl_add_u64 v[32:33], v[54:55], 0, v[184:185]
	v_lshl_add_u64 v[60:61], v[52:53], 0, v[72:73]
	v_lshl_add_u64 v[68:69], s[64:65], 0, v[88:89]
	v_cndmask_b32_e32 v44, v140, v156, vcc
	v_cndmask_b32_e32 v45, v141, v157, vcc
	v_cndmask_b32_e32 v46, v142, v158, vcc
	v_cndmask_b32_e32 v47, v143, v159, vcc
	v_cndmask_b32_e32 v40, v144, v160, vcc
	v_cndmask_b32_e32 v41, v145, v161, vcc
	v_cndmask_b32_e32 v42, v146, v162, vcc
	v_cndmask_b32_e32 v43, v147, v163, vcc
	v_cndmask_b32_e32 v36, v148, v164, vcc
	v_cndmask_b32_e32 v37, v149, v165, vcc
	v_cndmask_b32_e32 v38, v150, v166, vcc
	v_cndmask_b32_e32 v39, v151, v167, vcc
	v_cndmask_b32_e32 v32, v152, v168, vcc
	v_cndmask_b32_e32 v33, v153, v169, vcc
	v_cndmask_b32_e32 v34, v154, v170, vcc
	v_cndmask_b32_e32 v35, v155, v171, vcc
	s_nop 0
	s_nop 0
	flat_load_dwordx2 v[84:85], v[60:61] nt
	flat_load_dwordx2 v[80:81], v[60:61] offset:512 nt
	flat_load_dwordx2 v[76:77], v[60:61] offset:1024 nt
	flat_load_dwordx2 v[70:71], v[60:61] offset:1536 nt
	global_load_dwordx2 v[86:87], v[68:69], off nt
	global_load_dwordx2 v[82:83], v[68:69], off offset:512 nt
	global_load_dwordx2 v[78:79], v[68:69], off offset:1024 nt
	global_load_dwordx2 v[74:75], v[68:69], off offset:1536 nt
	v_or_b32_e32 v72, 0x200, v88
	v_lshl_add_u64 v[68:69], s[30:31], 0, v[72:73]
	v_or_b32_e32 v72, 0x400, v88
	v_lshl_add_u64 v[66:67], s[30:31], 0, v[88:89]
	v_lshl_add_u64 v[90:91], s[30:31], 0, v[72:73]
	v_or_b32_e32 v72, 0x600, v88
	v_lshl_add_u64 v[62:63], s[40:41], 0, v[184:185]
	v_lshlrev_b32_e32 v184, 2, v50
	v_lshl_add_u64 v[62:63], v[62:63], 0, v[184:185]
	v_add_co_u32_e32 v64, vcc, s1, v62
	v_lshl_add_u64 v[72:73], s[30:31], 0, v[72:73]
	s_nop 0
	v_addc_co_u32_e32 v65, vcc, 0, v63, vcc
	v_add_u32_e32 v48, s70, v48
	s_waitcnt vmcnt(0) lgkmcnt(0)
; DI float bf_lo(unsigned u) { return __uint_as_float(u << 16); }
; DI float bf_hi(unsigned u) { return __uint_as_float(u & 0xffff0000u); }
; DI void phase_row(const Params& P, const void* xs, int sh, void* xd, int dh, int ln, int gl, int gidx, float wgt, int modl, int shidx, bool dry = false) {
;     ...
;             const float* gate = mod + (gl * 2 + b) * 9216 + gidx * 1024;
; #pragma unroll
;             for (int j = 0; j < 4; ++j) { const f32x4 g = (*(const f32x4*)(gate + 4 * lane + 256 * j) + 1.f) * wgt;
;                 const f32x4 f = {bf_lo(fv[j].x), bf_hi(fv[j].x), bf_lo(fv[j].y), bf_hi(fv[j].y)};
;                 v[j] = v[j] * DN_ALPHA + g * f; }
;             float s = 0.f;
; #pragma unroll
;             for (int j = 0; j < 4; ++j) s += (v[j][0] + v[j][1]) + (v[j][2] + v[j][3]);
;             const float mean = wave_sum(s, lane) * (1.f / 1024.f);
;             float q = 0.f;
; #pragma unroll
;             for (int j = 0; j < 4; ++j) { v[j] = v[j] - mean; q += (v[j][0] * v[j][0] + v[j][1] * v[j][1]) + (v[j][2] * v[j][2] + v[j][3] * v[j][3]); }
	v_pk_add_f32 v[46:47], v[46:47], 1.0 op_sel_hi:[1,0]
	v_pk_add_f32 v[44:45], v[44:45], 1.0 op_sel_hi:[1,0]
	v_cvt_f32_f16_e32 v98, v86
	v_cvt_f32_f16_sdwa v99, v86 dst_sel:DWORD dst_unused:UNUSED_PAD src0_sel:WORD_1
	v_cvt_f32_f16_e32 v86, v87
	v_cvt_f32_f16_sdwa v87, v87 dst_sel:DWORD dst_unused:UNUSED_PAD src0_sel:WORD_1
	v_cvt_f32_f16_e32 v100, v82
	v_cvt_f32_f16_sdwa v101, v82 dst_sel:DWORD dst_unused:UNUSED_PAD src0_sel:WORD_1
	v_cvt_f32_f16_e32 v82, v83
	v_cvt_f32_f16_sdwa v83, v83 dst_sel:DWORD dst_unused:UNUSED_PAD src0_sel:WORD_1
	v_lshlrev_b32_e32 v88, 16, v84
	v_and_b32_e32 v89, 0xffff0000, v84
	v_lshlrev_b32_e32 v84, 16, v85
	v_and_b32_e32 v85, 0xffff0000, v85
	v_cvt_f32_f16_e32 v102, v78
	v_cvt_f32_f16_sdwa v103, v78 dst_sel:DWORD dst_unused:UNUSED_PAD src0_sel:WORD_1
	v_cvt_f32_f16_e32 v78, v79
	v_cvt_f32_f16_sdwa v79, v79 dst_sel:DWORD dst_unused:UNUSED_PAD src0_sel:WORD_1
	v_pk_add_f32 v[42:43], v[42:43], 1.0 op_sel_hi:[1,0]
	v_pk_add_f32 v[40:41], v[40:41], 1.0 op_sel_hi:[1,0]
	v_lshlrev_b32_e32 v92, 16, v80
	v_and_b32_e32 v93, 0xffff0000, v80
	v_lshlrev_b32_e32 v80, 16, v81
	v_and_b32_e32 v81, 0xffff0000, v81
	v_cvt_f32_f16_e32 v104, v74
	v_cvt_f32_f16_sdwa v105, v74 dst_sel:DWORD dst_unused:UNUSED_PAD src0_sel:WORD_1
	v_cvt_f32_f16_e32 v74, v75
	v_cvt_f32_f16_sdwa v75, v75 dst_sel:DWORD dst_unused:UNUSED_PAD src0_sel:WORD_1
	v_pk_mul_f32 v[46:47], v[46:47], v[84:85]
	v_pk_mul_f32 v[44:45], v[44:45], v[88:89]
	v_pk_add_f32 v[38:39], v[38:39], 1.0 op_sel_hi:[1,0]
	v_pk_add_f32 v[36:37], v[36:37], 1.0 op_sel_hi:[1,0]
	v_lshlrev_b32_e32 v94, 16, v76
	v_and_b32_e32 v95, 0xffff0000, v76
	v_lshlrev_b32_e32 v76, 16, v77
	v_and_b32_e32 v77, 0xffff0000, v77
	v_pk_mul_f32 v[42:43], v[42:43], v[80:81]
	v_pk_mul_f32 v[40:41], v[40:41], v[92:93]
	v_pk_fma_f32 v[46:47], v[86:87], s[42:43], v[46:47] op_sel_hi:[1,0,1]
	v_pk_fma_f32 v[44:45], v[98:99], s[42:43], v[44:45] op_sel_hi:[1,0,1]
	v_pk_add_f32 v[34:35], v[34:35], 1.0 op_sel_hi:[1,0]
	v_pk_add_f32 v[32:33], v[32:33], 1.0 op_sel_hi:[1,0]
	v_lshlrev_b32_e32 v96, 16, v70
	v_and_b32_e32 v97, 0xffff0000, v70
	v_lshlrev_b32_e32 v70, 16, v71
	v_and_b32_e32 v71, 0xffff0000, v71
	v_pk_mul_f32 v[38:39], v[38:39], v[76:77]
	v_pk_mul_f32 v[36:37], v[36:37], v[94:95]
	v_pk_fma_f32 v[42:43], v[82:83], s[42:43], v[42:43] op_sel_hi:[1,0,1]
	v_pk_fma_f32 v[40:41], v[100:101], s[42:43], v[40:41] op_sel_hi:[1,0,1]
	v_add_f32_e32 v49, v44, v45
	v_add_f32_e32 v51, v46, v47
	v_pk_mul_f32 v[34:35], v[34:35], v[70:71]
	v_pk_mul_f32 v[32:33], v[32:33], v[96:97]
	v_pk_fma_f32 v[38:39], v[78:79], s[42:43], v[38:39] op_sel_hi:[1,0,1]
	v_pk_fma_f32 v[36:37], v[102:103], s[42:43], v[36:37] op_sel_hi:[1,0,1]
	v_add_f32_e32 v70, v40, v41
	v_add_f32_e32 v71, v42, v43
	v_add_f32_e32 v49, v49, v51
	v_pk_fma_f32 v[34:35], v[74:75], s[42:43], v[34:35] op_sel_hi:[1,0,1]
	v_pk_fma_f32 v[32:33], v[104:105], s[42:43], v[32:33] op_sel_hi:[1,0,1]
	v_add_f32_e32 v74, v36, v37
	v_add_f32_e32 v75, v38, v39
	v_add_f32_e32 v51, v70, v71
	v_add_f32_e32 v49, 0, v49
	v_add_f32_e32 v76, v32, v33
	v_add_f32_e32 v77, v34, v35
	v_add_f32_e32 v70, v74, v75
	v_add_f32_e32 v49, v49, v51
	v_add_f32_e32 v71, v76, v77
	v_add_f32_e32 v49, v49, v70
	v_add_f32_e32 v49, v49, v71
	s_nop 1
	v_add_f32_dpp v49, v49, v49 quad_perm:[1,0,3,2] row_mask:0xf bank_mask:0xf bound_ctrl:1
	s_nop 1
	v_add_f32_dpp v49, v49, v49 quad_perm:[2,3,0,1] row_mask:0xf bank_mask:0xf bound_ctrl:1
	s_nop 1
	v_add_f32_dpp v49, v49, v49 row_half_mirror row_mask:0xf bank_mask:0xf bound_ctrl:1
	s_nop 1
	v_add_f32_dpp v49, v49, v49 row_mirror row_mask:0xf bank_mask:0xf bound_ctrl:1
	v_mov_b32_e32 v51, v49
	s_nop 1
	v_permlane16_swap_b32_e32 v49, v51
	v_add_f32_e32 v49, v49, v51
	v_mov_b32_e32 v51, v49
	s_nop 1
	v_permlane32_swap_b32_e32 v49, v51
	v_add_f32_e32 v49, v49, v51
	v_fmac_f32_e32 v47, 0xba800000, v49
	v_fmac_f32_e32 v45, 0xba800000, v49
	v_fmac_f32_e32 v43, 0xba800000, v49
	v_fmac_f32_e32 v41, 0xba800000, v49
	v_fmamk_f32 v46, v49, 0xba800000, v46
	v_fmamk_f32 v44, v49, 0xba800000, v44
	v_fmamk_f32 v42, v49, 0xba800000, v42
	v_fmamk_f32 v40, v49, 0xba800000, v40
	v_fmamk_f32 v38, v49, 0xba800000, v38
	v_fmac_f32_e32 v39, 0xba800000, v49
	v_fmamk_f32 v36, v49, 0xba800000, v36
	v_fmac_f32_e32 v37, 0xba800000, v49
	v_fmamk_f32 v34, v49, 0xba800000, v34
	v_fmac_f32_e32 v35, 0xba800000, v49
	v_fmamk_f32 v32, v49, 0xba800000, v32
	v_fmac_f32_e32 v33, 0xba800000, v49
	v_mul_f32_e32 v49, v45, v45
	v_mul_f32_e32 v51, v47, v47
	v_mul_f32_e32 v70, v41, v41
	v_mul_f32_e32 v71, v43, v43
	v_mul_f32_e32 v74, v37, v37
	v_mul_f32_e32 v75, v39, v39
; DI unsigned pk_bf16(float lo, float hi) { unsigned r; asm("v_cvt_pk_bf16_f32 %0, %1, %2" : "=v"(r) : "v"(lo), "v"(hi)); return r; }
; DI void phase_row(const Params& P, const void* xs, int sh, void* xd, int dh, int ln, int gl, int gidx, float wgt, int modl, int shidx, bool dry = false) {
;     ...
;             for (int j = 0; j < 4; ++j) { v[j] = v[j] - mean; q += (v[j][0] * v[j][0] + v[j][1] * v[j][1]) + (v[j][2] * v[j][2] + v[j][3] * v[j][3]); }
;             const float rstd = rsqrtf(wave_sum(q, lane) * (1.f / 1024.f) + LN_EPS);
; #pragma unroll
;             for (int j = 0; j < 4; ++j) { const f32x4 g = *(const f32x4*)(P.ln_g + ln * D + 4 * lane + 256 * j), bb = *(const f32x4*)(P.ln_b + ln * D + 4 * lane + 256 * j); v[j] = v[j] * rstd * g + bb; }
;             if (dry) { if (v[0][0] + v[1][1] + v[2][2] + v[3][3] == 12345.678f) P.xbuf[row] = 0.f; continue; }
; #pragma unroll
;             for (int j = 0; j < 4; ++j) { const size_t e = (size_t)row * D + 4 * lane + 256 * j;
;                 if (dh) __builtin_nontemporal_store(f4_to_h4(v[j]), (u32x2*)((unsigned short*)xd + e)); else __builtin_nontemporal_store(v[j], (f32x4*)((float*)xd + e)); }
;         }
;         if (modl >= 0) {
;             const float* shp = mod + (modl * 2 + b) * 9216 + shidx * 1024; const float* sc = shp + 1024;
; #pragma unroll
;             for (int j = 0; j < 4; ++j) { const f32x4 s4 = *(const f32x4*)(shp + 4 * lane + 256 * j), c4 = *(const f32x4*)(sc + 4 * lane + 256 * j);
;                 const f32x4 u = v[j] * (c4 + 1.f) + s4; u32x2 o; o.x = pk_bf16(u[0], u[1]); o.y = pk_bf16(u[2], u[3]);
;                 *(u32x2*)(U + (size_t)row * D + 4 * lane + 256 * j) = o; }
	v_fmac_f32_e32 v49, v44, v44
	v_fmac_f32_e32 v51, v46, v46
	v_fmac_f32_e32 v70, v40, v40
	v_fmac_f32_e32 v71, v42, v42
	v_mul_f32_e32 v76, v33, v33
	v_mul_f32_e32 v77, v35, v35
	v_fmac_f32_e32 v74, v36, v36
	v_fmac_f32_e32 v75, v38, v38
	v_add_f32_e32 v49, v49, v51
	v_add_f32_e32 v51, v70, v71
	v_fmac_f32_e32 v76, v32, v32
	v_fmac_f32_e32 v77, v34, v34
	v_add_f32_e32 v70, v74, v75
	v_add_f32_e32 v49, v49, v51
	v_add_f32_e32 v71, v76, v77
	v_add_f32_e32 v49, v70, v49
	v_add_f32_e32 v49, v71, v49
	s_nop 1
	v_add_f32_dpp v49, v49, v49 quad_perm:[1,0,3,2] row_mask:0xf bank_mask:0xf bound_ctrl:1
	s_nop 1
	v_add_f32_dpp v49, v49, v49 quad_perm:[2,3,0,1] row_mask:0xf bank_mask:0xf bound_ctrl:1
	s_nop 1
	v_add_f32_dpp v49, v49, v49 row_half_mirror row_mask:0xf bank_mask:0xf bound_ctrl:1
	s_nop 1
	v_add_f32_dpp v49, v49, v49 row_mirror row_mask:0xf bank_mask:0xf bound_ctrl:1
	v_mov_b32_e32 v51, v49
	s_nop 1
	v_permlane16_swap_b32_e32 v49, v51
	v_add_f32_e32 v49, v49, v51
	v_mov_b32_e32 v51, v49
	s_nop 1
	v_permlane32_swap_b32_e32 v49, v51
	v_add_f32_e32 v49, v49, v51
	v_fmamk_f32 v49, v49, 0x3a800000, v198
	v_mul_f32_e32 v51, 0x4b800000, v49
	v_cmp_gt_f32_e32 vcc, s25, v49
	s_nop 1
	v_cndmask_b32_e32 v49, v49, v51, vcc
	v_rsq_f32_e32 v49, v49
	s_nop 0
	v_mul_f32_e32 v51, 0x45800000, v49
	v_cndmask_b32_e32 v70, v49, v51, vcc
	v_pk_mul_f32 v[46:47], v[46:47], v[70:71] op_sel_hi:[1,0]
	v_pk_mul_f32 v[44:45], v[44:45], v[70:71] op_sel_hi:[1,0]
	v_pk_mul_f32 v[40:41], v[40:41], v[70:71] op_sel_hi:[1,0]
	v_pk_mul_f32 v[42:43], v[42:43], v[70:71] op_sel_hi:[1,0]
	v_pk_mul_f32 v[36:37], v[36:37], v[70:71] op_sel_hi:[1,0]
	v_pk_mul_f32 v[38:39], v[38:39], v[70:71] op_sel_hi:[1,0]
	v_pk_mul_f32 v[32:33], v[32:33], v[70:71] op_sel_hi:[1,0]
	v_pk_mul_f32 v[34:35], v[34:35], v[70:71] op_sel_hi:[1,0]
	v_pk_fma_f32 v[8:9], v[116:117], v[44:45], v[132:133]
	v_pk_fma_f32 v[10:11], v[118:119], v[46:47], v[134:135]
	v_pk_fma_f32 v[18:19], v[110:111], v[42:43], v[126:127]
	v_pk_fma_f32 v[16:17], v[108:109], v[40:41], v[124:125]
	v_pk_fma_f32 v[14:15], v[122:123], v[38:39], v[138:139]
	v_pk_fma_f32 v[12:13], v[120:121], v[36:37], v[136:137]
	v_pk_fma_f32 v[22:23], v[114:115], v[34:35], v[130:131]
	v_pk_fma_f32 v[20:21], v[112:113], v[32:33], v[128:129]
	v_cvt_pk_f16_f32 v1, v10, v11
	v_cvt_pk_f16_f32 v0, v8, v9
	v_cvt_pk_f16_f32 v3, v18, v19
	v_cvt_pk_f16_f32 v2, v16, v17
	v_cvt_pk_f16_f32 v5, v14, v15
	v_cvt_pk_f16_f32 v4, v12, v13
	v_cvt_pk_f16_f32 v7, v22, v23
	v_cvt_pk_f16_f32 v6, v20, v21
	flat_store_dwordx2 v[66:67], v[0:1] nt
	flat_store_dwordx2 v[68:69], v[2:3] nt
	flat_store_dwordx2 v[90:91], v[4:5] nt
	flat_store_dwordx2 v[72:73], v[6:7] nt
	flat_load_dwordx4 v[0:3], v[64:65]
	s_nop 0
	flat_load_dwordx4 v[4:7], v[62:63]
	v_lshl_add_u64 v[24:25], v[62:63], 0, s[46:47]
	v_cmp_lt_i32_e32 vcc, s20, v48
	s_or_b64 s[44:45], vcc, s[44:45]
	s_waitcnt vmcnt(0) lgkmcnt(0)
	v_pk_add_f32 v[0:1], v[0:1], 1.0 op_sel_hi:[1,0]
	v_pk_add_f32 v[2:3], v[2:3], 1.0 op_sel_hi:[1,0]
	v_pk_fma_f32 v[0:1], v[8:9], v[0:1], v[4:5]
	v_pk_fma_f32 v[2:3], v[10:11], v[2:3], v[6:7]
	v_cvt_pk_bf16_f32 v0, v0, v1
	s_nop 0
	v_cvt_pk_bf16_f32 v1, v2, v3
	flat_store_dwordx2 v[60:61], v[0:1]
	flat_load_dwordx4 v[0:3], v[24:25] offset:1024
	s_nop 0
	flat_load_dwordx4 v[4:7], v[62:63] offset:1024
	s_waitcnt vmcnt(0) lgkmcnt(0)
	v_pk_add_f32 v[0:1], v[0:1], 1.0 op_sel_hi:[1,0]
	v_pk_add_f32 v[2:3], v[2:3], 1.0 op_sel_hi:[1,0]
	v_pk_fma_f32 v[0:1], v[16:17], v[0:1], v[4:5]
	v_pk_fma_f32 v[2:3], v[18:19], v[2:3], v[6:7]
	v_cvt_pk_bf16_f32 v0, v0, v1
	s_nop 0
	v_cvt_pk_bf16_f32 v1, v2, v3
	flat_store_dwordx2 v[60:61], v[0:1] offset:512
	flat_load_dwordx4 v[0:3], v[24:25] offset:2048
	s_nop 0
	flat_load_dwordx4 v[4:7], v[62:63] offset:2048
	s_waitcnt vmcnt(0) lgkmcnt(0)
	v_pk_add_f32 v[0:1], v[0:1], 1.0 op_sel_hi:[1,0]
	v_pk_add_f32 v[2:3], v[2:3], 1.0 op_sel_hi:[1,0]
	v_pk_fma_f32 v[0:1], v[12:13], v[0:1], v[4:5]
	v_pk_fma_f32 v[2:3], v[14:15], v[2:3], v[6:7]
	v_cvt_pk_bf16_f32 v0, v0, v1
	s_nop 0
	v_cvt_pk_bf16_f32 v1, v2, v3
	flat_store_dwordx2 v[60:61], v[0:1] offset:1024
	flat_load_dwordx4 v[0:3], v[24:25] offset:3072
	s_nop 0
	flat_load_dwordx4 v[4:7], v[62:63] offset:3072
	s_waitcnt vmcnt(0) lgkmcnt(0)
	v_pk_add_f32 v[0:1], v[0:1], 1.0 op_sel_hi:[1,0]
	v_pk_add_f32 v[2:3], v[2:3], 1.0 op_sel_hi:[1,0]
	v_pk_fma_f32 v[0:1], v[20:21], v[0:1], v[4:5]
	v_pk_fma_f32 v[2:3], v[22:23], v[2:3], v[6:7]
	v_cvt_pk_bf16_f32 v0, v0, v1
	s_nop 0
	v_cvt_pk_bf16_f32 v1, v2, v3
	flat_store_dwordx2 v[60:61], v[0:1] offset:1536
	s_andn2_b64 exec, exec, s[44:45]
	s_cbranch_execnz .LBB0_23

; DI void attn_unit(const Params& P, LAS unsigned char* lds, int b, int h, int qb, bool dry) {
;     ...
;         float mx = fmaxf(fmaxf(s0[0], s0[1]), s0[2]);
; #pragma unroll
;         for (int i = 3; i < 15; i += 2) mx = fmaxf(fmaxf(mx, s0[i]), s0[i + 1]);
;         mx = fmaxf(fmaxf(mx, s0[15]), s1[0]);
; #pragma unroll
;         for (int i = 1; i < 15; i += 2) mx = fmaxf(fmaxf(mx, s1[i]), s1[i + 1]);
;         mx = fmaxf(mx, s1[15]);
;         { const auto rr = __builtin_amdgcn_permlane32_swap(__float_as_uint(mx), __float_as_uint(mx), false, false);
;           mx = fmaxf(__uint_as_float(rr[0]), __uint_as_float(rr[1])); }
;         if (__builtin_amdgcn_ballot_w64(mx > mrun + 8.f)) {
.LBB0_38:
	v_max_f32_e32 v221, v80, v81
	v_max3_f32 v221, v221, v82, v83
	v_max3_f32 v221, v221, v84, v85
	v_max3_f32 v221, v221, v86, v87
	v_max3_f32 v221, v221, v88, v89
	v_max3_f32 v221, v221, v90, v91
	v_max3_f32 v221, v221, v92, v93
	v_max3_f32 v221, v221, v94, v95
	v_max3_f32 v221, v221, v64, v65
	v_max3_f32 v221, v221, v66, v67
	v_max3_f32 v221, v221, v68, v69
	v_max3_f32 v221, v221, v70, v71
	v_max3_f32 v221, v221, v72, v73
	v_max3_f32 v221, v221, v74, v75
	v_max3_f32 v221, v221, v76, v77
	v_max3_f32 v221, v221, v78, v79
	v_mov_b32_e32 v222, v221
	s_nop 1
	v_permlane32_swap_b32_e32 v221, v222
	v_max_f32_e32 v221, v221, v222
	v_cmp_lt_f32_e32 vcc, 0x41000000, v221
	s_cmp_eq_u32 s20, 2
	s_cbranch_scc1 .Lfold_r0
	s_cbranch_vccz .LBB0_40

; #define ATT_LOAD(kr, vr, t) do { const bf16_t* kp_ = KVb + (size_t)(t) * 64 * 2048 + kn_off; \
;         kr[0] = *(const u32x4*)kp_; kr[1] = *(const u32x4*)(kp_ + 32 * 2048); kr[2] = *(const u32x4*)(KPEb + (t) * 64 * 64 + kp_off); \
;         const bf16_t* vp_ = VTb + (t) * 64 + v_off; vr[0] = *(const u32x4*)vp_; vr[1] = *(const u32x4*)(vp_ + 64 * SEQ); } while (0)
; #define ATT_TILE(t, slot) do { const int rel_ = (t) - 4 * qb; if (rel_ <= (w >> 1)) { qk_softmax((t), (slot), rel_ == (w >> 1)); pv(slot); } } while (0)
; DI void attn_unit(const Params& P, LAS unsigned char* lds, int b, int h, int qb, bool dry) {
;     ...
;     for (int kt = 0; kt < nt; kt += 2) {
;         const bool more2 = kt + 2 < nt;
;         if (more2) ATT_LOAD(kB, vB, kt + 2);
;         ATT_TILE(kt, 0);
;         ATT_STORE(kA, vA, 1);
;         __syncthreads();
;         if (more2) ATT_LOAD(kA, vA, kt + 3);
;         ATT_TILE(kt + 1, 1);
;         if (more2) ATT_STORE(kB, vB, 0);
;         __syncthreads();
.Lattn_wdone0:
	s_not_b64 s[40:41], s[52:53]
	s_andn2_b64 vcc, exec, s[52:53]
	s_waitcnt lgkmcnt(0)
	s_barrier
	s_cbranch_vccnz .LBB0_44
	v_add_co_u32_e32 v64, vcc, 0xfffe0000, v192
	s_nop 1
	v_addc_co_u32_e32 v65, vcc, -1, v193, vcc
	global_load_dwordx4 v[144:147], v[64:65], off
	global_load_dwordx4 v[148:151], v[192:193], off
	global_load_dwordx4 v[152:155], v[188:189], off
	v_add_co_u32_e32 v64, vcc, 0xffe00000, v190
	s_nop 1
	v_addc_co_u32_e32 v65, vcc, -1, v191, vcc
	global_load_dwordx4 v[156:159], v[64:65], off
	global_load_dwordx4 v[160:163], v[190:191], off
	s_add_i32 s80, s80, -1
	s_cmp_gt_i32 s80, s26
	s_cbranch_scc0 .LBB0_45

; DI void attn_unit(const Params& P, LAS unsigned char* lds, int b, int h, int qb, bool dry) {
;     ...
;         float mx = fmaxf(fmaxf(s0[0], s0[1]), s0[2]);
; #pragma unroll
;         for (int i = 3; i < 15; i += 2) mx = fmaxf(fmaxf(mx, s0[i]), s0[i + 1]);
;         mx = fmaxf(fmaxf(mx, s0[15]), s1[0]);
; #pragma unroll
;         for (int i = 1; i < 15; i += 2) mx = fmaxf(fmaxf(mx, s1[i]), s1[i + 1]);
;         mx = fmaxf(mx, s1[15]);
;         { const auto rr = __builtin_amdgcn_permlane32_swap(__float_as_uint(mx), __float_as_uint(mx), false, false);
;           mx = fmaxf(__uint_as_float(rr[0]), __uint_as_float(rr[1])); }
;         if (__builtin_amdgcn_ballot_w64(mx > mrun + 8.f)) {
.LBB0_47:
	s_nop 4
	v_max_f32_e32 v220, v80, v81
	v_max3_f32 v220, v220, v82, v83
	v_max3_f32 v220, v220, v84, v85
	v_max3_f32 v220, v220, v86, v87
	v_max3_f32 v220, v220, v88, v89
	v_max3_f32 v220, v220, v90, v91
	v_max3_f32 v220, v220, v92, v93
	v_max3_f32 v220, v220, v94, v95
	v_max3_f32 v220, v220, v64, v65
	v_max3_f32 v220, v220, v66, v67
	v_max3_f32 v220, v220, v68, v69
	v_max3_f32 v220, v220, v70, v71
	v_max3_f32 v220, v220, v72, v73
	v_max3_f32 v220, v220, v74, v75
	v_max3_f32 v220, v220, v76, v77
	v_max3_f32 v220, v220, v78, v79
	v_mov_b32_e32 v221, v220
	s_nop 1
	v_permlane32_swap_b32_e32 v220, v221
	v_max_f32_e32 v220, v220, v221
	v_cmp_lt_f32_e32 vcc, 0x41000000, v220
	s_cbranch_vccz .LBB0_49

; #define ATT_LOAD(kr, vr, t) do { const bf16_t* kp_ = KVb + (size_t)(t) * 64 * 2048 + kn_off; \
;         kr[0] = *(const u32x4*)kp_; kr[1] = *(const u32x4*)(kp_ + 32 * 2048); kr[2] = *(const u32x4*)(KPEb + (t) * 64 * 64 + kp_off); \
;         const bf16_t* vp_ = VTb + (t) * 64 + v_off; vr[0] = *(const u32x4*)vp_; vr[1] = *(const u32x4*)(vp_ + 64 * SEQ); } while (0)
; #define ATT_TILE(t, slot) do { const int rel_ = (t) - 4 * qb; if (rel_ <= (w >> 1)) { qk_softmax((t), (slot), rel_ == (w >> 1)); pv(slot); } } while (0)
; DI void attn_unit(const Params& P, LAS unsigned char* lds, int b, int h, int qb, bool dry) {
;     ...
;     for (int kt = 0; kt < nt; kt += 2) {
;         const bool more2 = kt + 2 < nt;
;         if (more2) ATT_LOAD(kB, vB, kt + 2);
;         ATT_TILE(kt, 0);
;         ATT_STORE(kA, vA, 1);
;         __syncthreads();
;         if (more2) ATT_LOAD(kA, vA, kt + 3);
;         ATT_TILE(kt + 1, 1);
;         if (more2) ATT_STORE(kB, vB, 0);
;         __syncthreads();
.Lattn_wdone2:
	s_not_b64 s[40:41], s[30:31]
	s_andn2_b64 vcc, exec, s[30:31]
	s_waitcnt lgkmcnt(0)
	s_barrier
	s_cbranch_vccnz .LBB0_64
	v_add_co_u32_e32 v64, vcc, 0xfffe0000, v192
	s_nop 1
	v_addc_co_u32_e32 v65, vcc, -1, v193, vcc
	global_load_dwordx4 v[144:147], v[64:65], off
	global_load_dwordx4 v[148:151], v[192:193], off
	global_load_dwordx4 v[152:155], v[188:189], off
	v_add_co_u32_e32 v64, vcc, 0xffe00000, v190
	s_nop 1
	v_addc_co_u32_e32 v65, vcc, -1, v191, vcc
	global_load_dwordx4 v[156:159], v[64:65], off
	global_load_dwordx4 v[160:163], v[190:191], off
	s_add_i32 s37, s37, -1
	s_cmp_gt_i32 s37, s36
	s_cbranch_scc0 .LBB0_65

; DI float bf_lo(unsigned u) { return __uint_as_float(u << 16); }
; DI float bf_hi(unsigned u) { return __uint_as_float(u & 0xffff0000u); }
; DI int obid() { int b = blockIdx.x; asm volatile("" : "+s"(b)); return b; }
; DI f32x4 h4_to_f4(u32x2 t) { const h16x4 h = __builtin_bit_cast(h16x4, t); return (f32x4){(float)h[0], (float)h[1], (float)h[2], (float)h[3]}; }
; DI void phase_row(const Params& P, const void* xs, int sh, void* xd, int dh, int ln, int gl, int gidx, float wgt, int modl, int shidx, bool dry = false) {
;     ...
;     for (int row = obid() * 8 + w; row < T; row += gridDim.x * 8) {
;         const int b = row >= SEQ;
;         f32x4 v[4];
; #pragma unroll
;         for (int j = 0; j < 4; ++j) { const size_t e = (size_t)row * D + 4 * lane + 256 * j;
;             if (sh) v[j] = h4_to_f4(__builtin_nontemporal_load((const u32x2*)((const unsigned short*)xs + e))); else v[j] = __builtin_nontemporal_load((const f32x4*)((const float*)xs + e)); }
;         if (ln >= 0) {
;             u32x2 fv[4];
; #pragma unroll
;             for (int j = 0; j < 4; ++j) fv[j] = __builtin_nontemporal_load((const u32x2*)(U + (size_t)row * D + 4 * lane + 256 * j));
;             const float* gate = mod + (gl * 2 + b) * 9216 + gidx * 1024;
; #pragma unroll
;             for (int j = 0; j < 4; ++j) { const f32x4 g = (*(const f32x4*)(gate + 4 * lane + 256 * j) + 1.f) * wgt;
;                 const f32x4 f = {bf_lo(fv[j].x), bf_hi(fv[j].x), bf_lo(fv[j].y), bf_hi(fv[j].y)};
;                 v[j] = v[j] * DN_ALPHA + g * f; }
.LBB0_95:
	s_and_b64 vcc, exec, s[2:3]
	s_cbranch_vccz .LBB0_101
	v_readlane_b32 s2, v245, 33
	s_cmp_eq_u32 s2, 17
	s_mov_b64 s[48:49], -1
	s_cbranch_scc0 .LBB0_101
	s_waitcnt vmcnt(0)
	v_mov_b32_e32 v0, v195
	s_load_dwordx8 s[40:47], s[84:85], 0xc8
	v_ashrrev_i32_e32 v1, 6, v0
	s_mov_b32 s2, s28
	s_waitcnt lgkmcnt(0)
	s_mov_b64 s[26:27], s[46:47]
	s_mov_b64 s[30:31], s[46:47]
	s_nop 0
	v_lshl_add_u32 v32, s2, 3, v1
	v_cmp_gt_i32_e32 vcc, s75, v32
	s_and_saveexec_b64 s[2:3], vcc
	s_mov_b32 s42, 0x3fb504f3
	s_mov_b64 s[44:45], 0x1000
	s_cbranch_execz .LBB0_100
	v_lshlrev_b32_e32 v0, 2, v0
	v_and_b32_e32 v0, 0xfc, v0
	v_lshlrev_b32_e32 v184, 1, v0
	s_load_dwordx16 s[48:63], s[84:85], 0x0
	v_lshl_add_u64 v[2:3], s[30:31], 0, v[184:185]
	s_mov_b64 s[30:31], 0x5808000
	s_waitcnt lgkmcnt(0)
	s_load_dwordx8 s[48:55], s[84:85], 0xc8
	v_lshl_add_u64 v[34:35], v[2:3], 0, s[30:31]
	v_lshlrev_b32_e32 v2, 2, v0
	v_mov_b32_e32 v3, v185
	v_lshl_add_u64 v[4:5], s[26:27], 0, v[2:3]
	s_mov_b64 s[30:31], 0x5582000
	v_lshl_add_u64 v[36:37], v[4:5], 0, s[30:31]
	s_add_u32 s30, s26, 0x5583000
	s_addc_u32 s31, s27, 0
	v_lshl_add_u64 v[4:5], s[62:63], 0, v[2:3]
	s_mov_b64 s[26:27], 0x3000
	v_lshl_add_u64 v[2:3], s[4:5], 0, v[2:3]
	s_mov_b64 s[60:61], 0
	v_lshl_add_u64 v[38:39], v[4:5], 0, s[26:27]
	v_lshl_add_u64 v[40:41], v[2:3], 0, s[26:27]
	s_waitcnt lgkmcnt(0)
	v_lshl_add_u64 v[42:43], s[52:53], 0, v[184:185]
	s_mov_b64 s[40:41], 0
	v_lshlrev_b32_e32 v44, 2, v0
	global_load_dwordx4 v[112:115], v[38:39], off
	global_load_dwordx4 v[104:107], v[38:39], off offset:1024
	global_load_dwordx4 v[128:131], v[40:41], off
	global_load_dwordx4 v[120:123], v[40:41], off offset:1024
	global_load_dwordx4 v[116:119], v[38:39], off offset:2048
	global_load_dwordx4 v[108:111], v[38:39], off offset:3072
	global_load_dwordx4 v[132:135], v[40:41], off offset:2048
	global_load_dwordx4 v[124:127], v[40:41], off offset:3072
	v_mov_b32_e32 v184, v196
	v_lshl_add_u64 v[102:103], v[36:37], 0, v[184:185]
	flat_load_dwordx4 v[136:139], v[102:103]
	flat_load_dwordx4 v[140:143], v[102:103] offset:1024
	flat_load_dwordx4 v[144:147], v[102:103] offset:2048
	flat_load_dwordx4 v[148:151], v[102:103] offset:3072
	v_mov_b32_e32 v184, v197
	v_lshl_add_u64 v[102:103], v[36:37], 0, v[184:185]
	flat_load_dwordx4 v[152:155], v[102:103]
	flat_load_dwordx4 v[156:159], v[102:103] offset:1024
	flat_load_dwordx4 v[160:163], v[102:103] offset:2048
	flat_load_dwordx4 v[164:167], v[102:103] offset:3072
	s_waitcnt vmcnt(0) lgkmcnt(0)
.LBB0_99:
	v_cmp_lt_i32_e32 vcc, s23, v32
	v_ashrrev_i32_e32 v33, 31, v32
	v_lshlrev_b64 v[48:49], 11, v[32:33]
	v_cndmask_b32_e32 v184, v196, v197, vcc
	v_lshl_add_u64 v[46:47], v[36:37], 0, v[184:185]
	v_mov_b32_e32 v45, v185
	v_lshl_add_u64 v[68:69], s[30:31], 0, v[184:185]
	v_cndmask_b32_e32 v52, v136, v152, vcc
	v_cndmask_b32_e32 v53, v137, v153, vcc
	v_cndmask_b32_e32 v54, v138, v154, vcc
	v_cndmask_b32_e32 v55, v139, v155, vcc
	v_cndmask_b32_e32 v56, v140, v156, vcc
	v_cndmask_b32_e32 v57, v141, v157, vcc
	v_cndmask_b32_e32 v58, v142, v158, vcc
	v_cndmask_b32_e32 v59, v143, v159, vcc
	v_cndmask_b32_e32 v60, v144, v160, vcc
	v_cndmask_b32_e32 v61, v145, v161, vcc
	v_cndmask_b32_e32 v62, v146, v162, vcc
	v_cndmask_b32_e32 v63, v147, v163, vcc
	v_cndmask_b32_e32 v64, v148, v164, vcc
	v_cndmask_b32_e32 v65, v149, v165, vcc
	v_cndmask_b32_e32 v66, v150, v166, vcc
	v_cndmask_b32_e32 v67, v151, v167, vcc
	v_lshl_add_u64 v[50:51], v[42:43], 0, v[48:49]
	v_lshl_add_u64 v[46:47], v[34:35], 0, v[48:49]
	v_lshl_add_u64 v[48:49], v[68:69], 0, v[44:45]
	global_load_dwordx2 v[68:69], v[50:51], off nt
	global_load_dwordx2 v[70:71], v[50:51], off offset:512 nt
	global_load_dwordx2 v[72:73], v[50:51], off offset:1024 nt
	global_load_dwordx2 v[74:75], v[50:51], off offset:1536 nt
	flat_load_dwordx2 v[76:77], v[46:47] nt
	flat_load_dwordx2 v[78:79], v[46:47] offset:512 nt
	flat_load_dwordx2 v[80:81], v[46:47] offset:1024 nt
	flat_load_dwordx2 v[82:83], v[46:47] offset:1536 nt
	v_add_co_u32_e32 v84, vcc, s1, v48
	v_add_u32_e32 v32, s70, v32
	s_nop 0
	v_addc_co_u32_e32 v85, vcc, 0, v49, vcc
	s_waitcnt vmcnt(0)
	v_cvt_f32_f16_e32 v86, v68
	v_cvt_f32_f16_sdwa v87, v68 dst_sel:DWORD dst_unused:UNUSED_PAD src0_sel:WORD_1
	v_cvt_f32_f16_e32 v68, v69
	v_cvt_f32_f16_sdwa v69, v69 dst_sel:DWORD dst_unused:UNUSED_PAD src0_sel:WORD_1
	s_waitcnt lgkmcnt(0)
; DI float bf_lo(unsigned u) { return __uint_as_float(u << 16); }
; DI float bf_hi(unsigned u) { return __uint_as_float(u & 0xffff0000u); }
; DI void phase_row(const Params& P, const void* xs, int sh, void* xd, int dh, int ln, int gl, int gidx, float wgt, int modl, int shidx, bool dry = false) {
;     ...
;             const float* gate = mod + (gl * 2 + b) * 9216 + gidx * 1024;
; #pragma unroll
;             for (int j = 0; j < 4; ++j) { const f32x4 g = (*(const f32x4*)(gate + 4 * lane + 256 * j) + 1.f) * wgt;
;                 const f32x4 f = {bf_lo(fv[j].x), bf_hi(fv[j].x), bf_lo(fv[j].y), bf_hi(fv[j].y)};
;                 v[j] = v[j] * DN_ALPHA + g * f; }
;             float s = 0.f;
; #pragma unroll
;             for (int j = 0; j < 4; ++j) s += (v[j][0] + v[j][1]) + (v[j][2] + v[j][3]);
;             const float mean = wave_sum(s, lane) * (1.f / 1024.f);
;             float q = 0.f;
; #pragma unroll
;             for (int j = 0; j < 4; ++j) { v[j] = v[j] - mean; q += (v[j][0] * v[j][0] + v[j][1] * v[j][1]) + (v[j][2] * v[j][2] + v[j][3] * v[j][3]); }
	v_pk_add_f32 v[54:55], v[54:55], 1.0 op_sel_hi:[1,0]
	v_pk_add_f32 v[52:53], v[52:53], 1.0 op_sel_hi:[1,0]
	v_cvt_f32_f16_e32 v88, v70
	v_cvt_f32_f16_sdwa v89, v70 dst_sel:DWORD dst_unused:UNUSED_PAD src0_sel:WORD_1
	v_cvt_f32_f16_e32 v70, v71
	v_cvt_f32_f16_sdwa v71, v71 dst_sel:DWORD dst_unused:UNUSED_PAD src0_sel:WORD_1
	v_pk_add_f32 v[58:59], v[58:59], 1.0 op_sel_hi:[1,0]
	v_pk_add_f32 v[56:57], v[56:57], 1.0 op_sel_hi:[1,0]
	v_cvt_f32_f16_e32 v90, v72
	v_cvt_f32_f16_sdwa v91, v72 dst_sel:DWORD dst_unused:UNUSED_PAD src0_sel:WORD_1
	v_cvt_f32_f16_e32 v72, v73
	v_cvt_f32_f16_sdwa v73, v73 dst_sel:DWORD dst_unused:UNUSED_PAD src0_sel:WORD_1
	v_lshlrev_b32_e32 v94, 16, v76
	v_and_b32_e32 v95, 0xffff0000, v76
	v_lshlrev_b32_e32 v76, 16, v77
	v_and_b32_e32 v77, 0xffff0000, v77
	v_pk_mul_f32 v[54:55], v[54:55], 0.5 op_sel_hi:[1,0]
	v_pk_mul_f32 v[52:53], v[52:53], 0.5 op_sel_hi:[1,0]
	v_pk_add_f32 v[62:63], v[62:63], 1.0 op_sel_hi:[1,0]
	v_pk_add_f32 v[60:61], v[60:61], 1.0 op_sel_hi:[1,0]
	v_cvt_f32_f16_e32 v92, v74
	v_cvt_f32_f16_sdwa v93, v74 dst_sel:DWORD dst_unused:UNUSED_PAD src0_sel:WORD_1
	v_cvt_f32_f16_e32 v74, v75
	v_cvt_f32_f16_sdwa v75, v75 dst_sel:DWORD dst_unused:UNUSED_PAD src0_sel:WORD_1
	v_lshlrev_b32_e32 v96, 16, v78
	v_and_b32_e32 v97, 0xffff0000, v78
	v_lshlrev_b32_e32 v78, 16, v79
	v_and_b32_e32 v79, 0xffff0000, v79
	v_pk_mul_f32 v[58:59], v[58:59], 0.5 op_sel_hi:[1,0]
	v_pk_mul_f32 v[56:57], v[56:57], 0.5 op_sel_hi:[1,0]
	v_pk_mul_f32 v[54:55], v[54:55], v[76:77]
	v_pk_mul_f32 v[52:53], v[52:53], v[94:95]
	v_pk_add_f32 v[66:67], v[66:67], 1.0 op_sel_hi:[1,0]
	v_pk_add_f32 v[64:65], v[64:65], 1.0 op_sel_hi:[1,0]
	v_lshlrev_b32_e32 v98, 16, v80
	v_and_b32_e32 v99, 0xffff0000, v80
	v_lshlrev_b32_e32 v80, 16, v81
	v_and_b32_e32 v81, 0xffff0000, v81
	v_pk_mul_f32 v[62:63], v[62:63], 0.5 op_sel_hi:[1,0]
	v_pk_mul_f32 v[60:61], v[60:61], 0.5 op_sel_hi:[1,0]
	v_pk_mul_f32 v[58:59], v[58:59], v[78:79]
	v_pk_mul_f32 v[56:57], v[56:57], v[96:97]
	v_pk_fma_f32 v[54:55], v[68:69], s[42:43], v[54:55] op_sel_hi:[1,0,1]
	v_pk_fma_f32 v[52:53], v[86:87], s[42:43], v[52:53] op_sel_hi:[1,0,1]
	v_lshlrev_b32_e32 v100, 16, v82
	v_and_b32_e32 v101, 0xffff0000, v82
	v_lshlrev_b32_e32 v82, 16, v83
	v_and_b32_e32 v83, 0xffff0000, v83
	v_pk_mul_f32 v[66:67], v[66:67], 0.5 op_sel_hi:[1,0]
	v_pk_mul_f32 v[64:65], v[64:65], 0.5 op_sel_hi:[1,0]
	v_pk_mul_f32 v[62:63], v[62:63], v[80:81]
	v_pk_mul_f32 v[60:61], v[60:61], v[98:99]
	v_pk_fma_f32 v[58:59], v[70:71], s[42:43], v[58:59] op_sel_hi:[1,0,1]
	v_pk_fma_f32 v[56:57], v[88:89], s[42:43], v[56:57] op_sel_hi:[1,0,1]
	v_add_f32_e32 v33, v52, v53
	v_add_f32_e32 v45, v54, v55
	v_pk_mul_f32 v[66:67], v[66:67], v[82:83]
	v_pk_mul_f32 v[64:65], v[64:65], v[100:101]
	v_pk_fma_f32 v[62:63], v[72:73], s[42:43], v[62:63] op_sel_hi:[1,0,1]
	v_pk_fma_f32 v[60:61], v[90:91], s[42:43], v[60:61] op_sel_hi:[1,0,1]
	v_add_f32_e32 v68, v56, v57
	v_add_f32_e32 v69, v58, v59
	v_add_f32_e32 v33, v33, v45
	v_pk_fma_f32 v[66:67], v[74:75], s[42:43], v[66:67] op_sel_hi:[1,0,1]
	v_pk_fma_f32 v[64:65], v[92:93], s[42:43], v[64:65] op_sel_hi:[1,0,1]
	v_add_f32_e32 v70, v60, v61
	v_add_f32_e32 v71, v62, v63
	v_add_f32_e32 v45, v68, v69
	v_add_f32_e32 v33, 0, v33
	v_add_f32_e32 v72, v64, v65
	v_add_f32_e32 v73, v66, v67
	v_add_f32_e32 v68, v70, v71
	v_add_f32_e32 v33, v33, v45
	v_add_f32_e32 v69, v72, v73
	v_add_f32_e32 v33, v33, v68
	v_add_f32_e32 v33, v33, v69
	s_nop 1
	v_add_f32_dpp v33, v33, v33 quad_perm:[1,0,3,2] row_mask:0xf bank_mask:0xf bound_ctrl:1
	s_nop 1
	v_add_f32_dpp v33, v33, v33 quad_perm:[2,3,0,1] row_mask:0xf bank_mask:0xf bound_ctrl:1
	s_nop 1
	v_add_f32_dpp v33, v33, v33 row_half_mirror row_mask:0xf bank_mask:0xf bound_ctrl:1
	s_nop 1
	v_add_f32_dpp v33, v33, v33 row_mirror row_mask:0xf bank_mask:0xf bound_ctrl:1
	v_mov_b32_e32 v45, v33
	s_nop 1
	v_permlane16_swap_b32_e32 v33, v45
	v_add_f32_e32 v33, v33, v45
	v_mov_b32_e32 v45, v33
	s_nop 1
	v_permlane32_swap_b32_e32 v33, v45
	v_add_f32_e32 v33, v33, v45
	v_fmac_f32_e32 v55, 0xba800000, v33
	v_fmac_f32_e32 v53, 0xba800000, v33
	v_fmac_f32_e32 v59, 0xba800000, v33
	v_fmac_f32_e32 v57, 0xba800000, v33
	v_fmamk_f32 v54, v33, 0xba800000, v54
	v_fmamk_f32 v52, v33, 0xba800000, v52
	v_fmamk_f32 v58, v33, 0xba800000, v58
	v_fmamk_f32 v56, v33, 0xba800000, v56
	v_fmamk_f32 v62, v33, 0xba800000, v62
	v_fmac_f32_e32 v63, 0xba800000, v33
	v_fmamk_f32 v60, v33, 0xba800000, v60
	v_fmac_f32_e32 v61, 0xba800000, v33
	v_fmamk_f32 v66, v33, 0xba800000, v66
	v_fmac_f32_e32 v67, 0xba800000, v33
	v_fmamk_f32 v64, v33, 0xba800000, v64
	v_fmac_f32_e32 v65, 0xba800000, v33
	v_mul_f32_e32 v33, v53, v53
	v_mul_f32_e32 v45, v55, v55
	v_mul_f32_e32 v68, v57, v57
	v_mul_f32_e32 v69, v59, v59
; DI unsigned pk_bf16(float lo, float hi) { unsigned r; asm("v_cvt_pk_bf16_f32 %0, %1, %2" : "=v"(r) : "v"(lo), "v"(hi)); return r; }
; DI void phase_row(const Params& P, const void* xs, int sh, void* xd, int dh, int ln, int gl, int gidx, float wgt, int modl, int shidx, bool dry = false) {
;     ...
;             for (int j = 0; j < 4; ++j) { v[j] = v[j] - mean; q += (v[j][0] * v[j][0] + v[j][1] * v[j][1]) + (v[j][2] * v[j][2] + v[j][3] * v[j][3]); }
;             const float rstd = rsqrtf(wave_sum(q, lane) * (1.f / 1024.f) + LN_EPS);
; #pragma unroll
;             for (int j = 0; j < 4; ++j) { const f32x4 g = *(const f32x4*)(P.ln_g + ln * D + 4 * lane + 256 * j), bb = *(const f32x4*)(P.ln_b + ln * D + 4 * lane + 256 * j); v[j] = v[j] * rstd * g + bb; }
;             if (dry) { if (v[0][0] + v[1][1] + v[2][2] + v[3][3] == 12345.678f) P.xbuf[row] = 0.f; continue; }
; #pragma unroll
;             for (int j = 0; j < 4; ++j) { const size_t e = (size_t)row * D + 4 * lane + 256 * j;
;                 if (dh) __builtin_nontemporal_store(f4_to_h4(v[j]), (u32x2*)((unsigned short*)xd + e)); else __builtin_nontemporal_store(v[j], (f32x4*)((float*)xd + e)); }
;         }
;         if (modl >= 0) {
;             const float* shp = mod + (modl * 2 + b) * 9216 + shidx * 1024; const float* sc = shp + 1024;
; #pragma unroll
;             for (int j = 0; j < 4; ++j) { const f32x4 s4 = *(const f32x4*)(shp + 4 * lane + 256 * j), c4 = *(const f32x4*)(sc + 4 * lane + 256 * j);
;                 const f32x4 u = v[j] * (c4 + 1.f) + s4; u32x2 o; o.x = pk_bf16(u[0], u[1]); o.y = pk_bf16(u[2], u[3]);
;                 *(u32x2*)(U + (size_t)row * D + 4 * lane + 256 * j) = o; }
	v_mul_f32_e32 v70, v61, v61
	v_mul_f32_e32 v71, v63, v63
	v_fmac_f32_e32 v33, v52, v52
	v_fmac_f32_e32 v45, v54, v54
	v_fmac_f32_e32 v68, v56, v56
	v_fmac_f32_e32 v69, v58, v58
	v_mul_f32_e32 v72, v65, v65
	v_mul_f32_e32 v73, v67, v67
	v_fmac_f32_e32 v70, v60, v60
	v_fmac_f32_e32 v71, v62, v62
	v_add_f32_e32 v33, v33, v45
	v_add_f32_e32 v45, v68, v69
	v_fmac_f32_e32 v72, v64, v64
	v_fmac_f32_e32 v73, v66, v66
	v_add_f32_e32 v68, v70, v71
	v_add_f32_e32 v33, v33, v45
	v_add_f32_e32 v69, v72, v73
	v_add_f32_e32 v33, v68, v33
	v_add_f32_e32 v33, v69, v33
	s_nop 1
	v_add_f32_dpp v33, v33, v33 quad_perm:[1,0,3,2] row_mask:0xf bank_mask:0xf bound_ctrl:1
	s_nop 1
	v_add_f32_dpp v33, v33, v33 quad_perm:[2,3,0,1] row_mask:0xf bank_mask:0xf bound_ctrl:1
	s_nop 1
	v_add_f32_dpp v33, v33, v33 row_half_mirror row_mask:0xf bank_mask:0xf bound_ctrl:1
	s_nop 1
	v_add_f32_dpp v33, v33, v33 row_mirror row_mask:0xf bank_mask:0xf bound_ctrl:1
	v_mov_b32_e32 v45, v33
	s_nop 1
	v_permlane16_swap_b32_e32 v33, v45
	v_add_f32_e32 v33, v33, v45
	v_mov_b32_e32 v45, v33
	s_nop 1
	v_permlane32_swap_b32_e32 v33, v45
	v_add_f32_e32 v33, v33, v45
	v_fmamk_f32 v33, v33, 0x3a800000, v198
	v_mul_f32_e32 v45, 0x4b800000, v33
	v_cmp_gt_f32_e32 vcc, s25, v33
	s_nop 1
	v_cndmask_b32_e32 v33, v33, v45, vcc
	v_rsq_f32_e32 v33, v33
	s_nop 0
	v_mul_f32_e32 v45, 0x45800000, v33
	v_cndmask_b32_e32 v68, v33, v45, vcc
	v_pk_mul_f32 v[54:55], v[54:55], v[68:69] op_sel_hi:[1,0]
	v_pk_mul_f32 v[52:53], v[52:53], v[68:69] op_sel_hi:[1,0]
	v_pk_mul_f32 v[56:57], v[56:57], v[68:69] op_sel_hi:[1,0]
	v_pk_mul_f32 v[58:59], v[58:59], v[68:69] op_sel_hi:[1,0]
	v_pk_mul_f32 v[60:61], v[60:61], v[68:69] op_sel_hi:[1,0]
	v_pk_mul_f32 v[62:63], v[62:63], v[68:69] op_sel_hi:[1,0]
	v_pk_mul_f32 v[64:65], v[64:65], v[68:69] op_sel_hi:[1,0]
	v_pk_mul_f32 v[66:67], v[66:67], v[68:69] op_sel_hi:[1,0]
	v_pk_fma_f32 v[8:9], v[112:113], v[52:53], v[128:129]
	v_pk_fma_f32 v[10:11], v[114:115], v[54:55], v[130:131]
	v_pk_fma_f32 v[18:19], v[106:107], v[58:59], v[122:123]
	v_pk_fma_f32 v[16:17], v[104:105], v[56:57], v[120:121]
	v_pk_fma_f32 v[14:15], v[118:119], v[62:63], v[134:135]
	v_pk_fma_f32 v[12:13], v[116:117], v[60:61], v[132:133]
	v_pk_fma_f32 v[22:23], v[110:111], v[66:67], v[126:127]
	v_pk_fma_f32 v[20:21], v[108:109], v[64:65], v[124:125]
	v_cvt_pk_f16_f32 v1, v10, v11
	v_cvt_pk_f16_f32 v0, v8, v9
	v_cvt_pk_f16_f32 v3, v18, v19
	v_cvt_pk_f16_f32 v2, v16, v17
	v_cvt_pk_f16_f32 v5, v14, v15
	v_cvt_pk_f16_f32 v4, v12, v13
	v_cvt_pk_f16_f32 v7, v22, v23
	v_cvt_pk_f16_f32 v6, v20, v21
	global_store_dwordx2 v[50:51], v[0:1], off nt
	global_store_dwordx2 v[50:51], v[2:3], off offset:512 nt
	global_store_dwordx2 v[50:51], v[4:5], off offset:1024 nt
	global_store_dwordx2 v[50:51], v[6:7], off offset:1536 nt
	flat_load_dwordx4 v[0:3], v[84:85]
	s_nop 0
	flat_load_dwordx4 v[4:7], v[48:49]
	v_lshl_add_u64 v[24:25], v[48:49], 0, s[44:45]
	v_cmp_lt_i32_e32 vcc, s20, v32
	s_or_b64 s[40:41], vcc, s[40:41]
	s_waitcnt vmcnt(0) lgkmcnt(0)
	v_pk_add_f32 v[0:1], v[0:1], 1.0 op_sel_hi:[1,0]
	v_pk_add_f32 v[2:3], v[2:3], 1.0 op_sel_hi:[1,0]
	v_pk_fma_f32 v[0:1], v[8:9], v[0:1], v[4:5]
	v_pk_fma_f32 v[2:3], v[10:11], v[2:3], v[6:7]
	v_cvt_pk_bf16_f32 v0, v0, v1
	s_nop 0
	v_cvt_pk_bf16_f32 v1, v2, v3
	flat_store_dwordx2 v[46:47], v[0:1]
	flat_load_dwordx4 v[0:3], v[24:25] offset:1024
	s_nop 0
	flat_load_dwordx4 v[4:7], v[48:49] offset:1024
	s_waitcnt vmcnt(0) lgkmcnt(0)
	v_pk_add_f32 v[0:1], v[0:1], 1.0 op_sel_hi:[1,0]
	v_pk_add_f32 v[2:3], v[2:3], 1.0 op_sel_hi:[1,0]
	v_pk_fma_f32 v[0:1], v[16:17], v[0:1], v[4:5]
	v_pk_fma_f32 v[2:3], v[18:19], v[2:3], v[6:7]
	v_cvt_pk_bf16_f32 v0, v0, v1
	s_nop 0
	v_cvt_pk_bf16_f32 v1, v2, v3
	flat_store_dwordx2 v[46:47], v[0:1] offset:512
	flat_load_dwordx4 v[0:3], v[24:25] offset:2048
	s_nop 0
	flat_load_dwordx4 v[4:7], v[48:49] offset:2048
	s_waitcnt vmcnt(0) lgkmcnt(0)
	v_pk_add_f32 v[0:1], v[0:1], 1.0 op_sel_hi:[1,0]
	v_pk_add_f32 v[2:3], v[2:3], 1.0 op_sel_hi:[1,0]
	v_pk_fma_f32 v[0:1], v[12:13], v[0:1], v[4:5]
	v_pk_fma_f32 v[2:3], v[14:15], v[2:3], v[6:7]
	v_cvt_pk_bf16_f32 v0, v0, v1
	s_nop 0
	v_cvt_pk_bf16_f32 v1, v2, v3
	flat_store_dwordx2 v[46:47], v[0:1] offset:1024
	flat_load_dwordx4 v[0:3], v[24:25] offset:3072
	s_nop 0
	flat_load_dwordx4 v[4:7], v[48:49] offset:3072
	s_waitcnt vmcnt(0) lgkmcnt(0)
	v_pk_add_f32 v[0:1], v[0:1], 1.0 op_sel_hi:[1,0]
	v_pk_add_f32 v[2:3], v[2:3], 1.0 op_sel_hi:[1,0]
	v_pk_fma_f32 v[0:1], v[20:21], v[0:1], v[4:5]
	v_pk_fma_f32 v[2:3], v[22:23], v[2:3], v[6:7]
	v_cvt_pk_bf16_f32 v0, v0, v1
	s_nop 0
	v_cvt_pk_bf16_f32 v1, v2, v3
	flat_store_dwordx2 v[46:47], v[0:1] offset:1536
	s_andn2_b64 exec, exec, s[40:41]
	s_cbranch_execnz .LBB0_99

; DI float bf_lo(unsigned u) { return __uint_as_float(u << 16); }
; DI float bf_hi(unsigned u) { return __uint_as_float(u & 0xffff0000u); }
; DI int obid() { int b = blockIdx.x; asm volatile("" : "+s"(b)); return b; }
; DI f32x4 h4_to_f4(u32x2 t) { const h16x4 h = __builtin_bit_cast(h16x4, t); return (f32x4){(float)h[0], (float)h[1], (float)h[2], (float)h[3]}; }
; DI void phase_row(const Params& P, const void* xs, int sh, void* xd, int dh, int ln, int gl, int gidx, float wgt, int modl, int shidx, bool dry = false) {
;     ...
;     for (int row = obid() * 8 + w; row < T; row += gridDim.x * 8) {
;         const int b = row >= SEQ;
;         f32x4 v[4];
; #pragma unroll
;         for (int j = 0; j < 4; ++j) { const size_t e = (size_t)row * D + 4 * lane + 256 * j;
;             if (sh) v[j] = h4_to_f4(__builtin_nontemporal_load((const u32x2*)((const unsigned short*)xs + e))); else v[j] = __builtin_nontemporal_load((const f32x4*)((const float*)xs + e)); }
;         if (ln >= 0) {
;             u32x2 fv[4];
; #pragma unroll
;             for (int j = 0; j < 4; ++j) fv[j] = __builtin_nontemporal_load((const u32x2*)(U + (size_t)row * D + 4 * lane + 256 * j));
;             const float* gate = mod + (gl * 2 + b) * 9216 + gidx * 1024;
; #pragma unroll
;             for (int j = 0; j < 4; ++j) { const f32x4 g = (*(const f32x4*)(gate + 4 * lane + 256 * j) + 1.f) * wgt;
;                 const f32x4 f = {bf_lo(fv[j].x), bf_hi(fv[j].x), bf_lo(fv[j].y), bf_hi(fv[j].y)};
;                 v[j] = v[j] * DN_ALPHA + g * f; }
.LBB0_102:
	s_and_b64 vcc, exec, s[2:3]
	s_cbranch_vccz .LBB0_116
	v_readlane_b32 s2, v245, 33
	s_cmp_gt_i32 s2, 13
	s_mov_b64 s[2:3], -1
	s_cbranch_scc0 .LBB0_110
	v_readlane_b32 s2, v245, 33
	s_cmp_eq_u32 s2, 14
	s_mov_b64 s[48:49], -1
	s_cbranch_scc0 .LBB0_109
	s_waitcnt vmcnt(0)
	v_mov_b32_e32 v0, v195
	s_load_dwordx8 s[40:47], s[84:85], 0xc8
	v_ashrrev_i32_e32 v1, 6, v0
	s_mov_b32 s2, s28
	s_waitcnt lgkmcnt(0)
	s_mov_b64 s[26:27], s[46:47]
	s_mov_b64 s[40:41], s[46:47]
	s_nop 0
	v_lshl_add_u32 v32, s2, 3, v1
	v_cmp_gt_i32_e32 vcc, s75, v32
	s_and_saveexec_b64 s[2:3], vcc
	s_mov_b32 s42, 0x3fb504f3
	s_mov_b64 s[44:45], 0x1000
	s_cbranch_execz .LBB0_108
	v_lshlrev_b32_e32 v0, 2, v0
	v_and_b32_e32 v0, 0xfc, v0
	s_load_dwordx16 s[48:63], s[84:85], 0x0
	v_lshlrev_b32_e32 v184, 1, v0
	s_waitcnt lgkmcnt(0)
	s_load_dwordx8 s[48:55], s[84:85], 0xc8
	v_lshl_add_u64 v[2:3], s[40:41], 0, v[184:185]
	s_mov_b64 s[36:37], 0x5808000
	s_add_u32 s30, s26, 0x5580000
	v_lshl_add_u64 v[34:35], v[2:3], 0, s[36:37]
	v_lshlrev_b32_e32 v2, 2, v0
	v_mov_b32_e32 v3, v185
	s_addc_u32 s31, s27, 0
	v_lshl_add_u64 v[4:5], s[26:27], 0, v[2:3]
	s_mov_b64 s[26:27], 0x5588000
	v_lshl_add_u64 v[36:37], v[4:5], 0, s[26:27]
	v_lshl_add_u64 v[4:5], s[62:63], 0, v[2:3]
	s_mov_b64 s[26:27], 0x2000
	v_lshl_add_u64 v[2:3], s[4:5], 0, v[2:3]
	s_mov_b64 s[60:61], 0
	v_lshl_add_u64 v[38:39], v[4:5], 0, s[26:27]
	v_lshl_add_u64 v[40:41], v[2:3], 0, s[26:27]
	s_waitcnt lgkmcnt(0)
	v_lshl_add_u64 v[42:43], s[52:53], 0, v[184:185]
	s_mov_b64 s[40:41], 0
	v_lshlrev_b32_e32 v44, 2, v0
	global_load_dwordx4 v[112:115], v[38:39], off
	global_load_dwordx4 v[104:107], v[38:39], off offset:1024
	global_load_dwordx4 v[128:131], v[40:41], off
	global_load_dwordx4 v[120:123], v[40:41], off offset:1024
	global_load_dwordx4 v[116:119], v[38:39], off offset:2048
	global_load_dwordx4 v[108:111], v[38:39], off offset:3072
	global_load_dwordx4 v[132:135], v[40:41], off offset:2048
	global_load_dwordx4 v[124:127], v[40:41], off offset:3072
	v_mov_b32_e32 v184, 0
	v_lshl_add_u64 v[102:103], v[36:37], 0, v[184:185]
	flat_load_dwordx4 v[136:139], v[102:103]
	flat_load_dwordx4 v[140:143], v[102:103] offset:1024
	flat_load_dwordx4 v[144:147], v[102:103] offset:2048
	flat_load_dwordx4 v[148:151], v[102:103] offset:3072
	v_mov_b32_e32 v184, v203
	v_lshl_add_u64 v[102:103], v[36:37], 0, v[184:185]
	flat_load_dwordx4 v[152:155], v[102:103]
	flat_load_dwordx4 v[156:159], v[102:103] offset:1024
	flat_load_dwordx4 v[160:163], v[102:103] offset:2048
	flat_load_dwordx4 v[164:167], v[102:103] offset:3072
	s_waitcnt vmcnt(0) lgkmcnt(0)
.LBB0_107:
	v_cmp_lt_i32_e32 vcc, s23, v32
	v_ashrrev_i32_e32 v33, 31, v32
	v_lshlrev_b64 v[48:49], 11, v[32:33]
	v_cndmask_b32_e32 v184, 0, v203, vcc
	v_lshl_add_u64 v[46:47], v[36:37], 0, v[184:185]
	v_cndmask_b32_e32 v52, v136, v152, vcc
	v_cndmask_b32_e32 v53, v137, v153, vcc
	v_cndmask_b32_e32 v54, v138, v154, vcc
	v_cndmask_b32_e32 v55, v139, v155, vcc
	v_cndmask_b32_e32 v56, v140, v156, vcc
	v_cndmask_b32_e32 v57, v141, v157, vcc
	v_cndmask_b32_e32 v58, v142, v158, vcc
	v_cndmask_b32_e32 v59, v143, v159, vcc
	v_cndmask_b32_e32 v60, v144, v160, vcc
	v_cndmask_b32_e32 v61, v145, v161, vcc
	v_cndmask_b32_e32 v62, v146, v162, vcc
	v_cndmask_b32_e32 v63, v147, v163, vcc
	v_cndmask_b32_e32 v64, v148, v164, vcc
	v_cndmask_b32_e32 v65, v149, v165, vcc
	v_cndmask_b32_e32 v66, v150, v166, vcc
	v_cndmask_b32_e32 v67, v151, v167, vcc
	v_lshl_add_u64 v[50:51], v[42:43], 0, v[48:49]
	v_lshl_add_u64 v[46:47], v[34:35], 0, v[48:49]
	global_load_dwordx2 v[68:69], v[50:51], off nt
	global_load_dwordx2 v[70:71], v[50:51], off offset:512 nt
	global_load_dwordx2 v[72:73], v[50:51], off offset:1024 nt
	global_load_dwordx2 v[74:75], v[50:51], off offset:1536 nt
	flat_load_dwordx2 v[76:77], v[46:47] nt
	flat_load_dwordx2 v[78:79], v[46:47] offset:512 nt
	flat_load_dwordx2 v[80:81], v[46:47] offset:1024 nt
	flat_load_dwordx2 v[82:83], v[46:47] offset:1536 nt
	v_cndmask_b32_e32 v184, v196, v197, vcc
	v_mov_b32_e32 v45, v185
	v_lshl_add_u64 v[48:49], s[30:31], 0, v[184:185]
	v_lshl_add_u64 v[48:49], v[48:49], 0, v[44:45]
	v_add_co_u32_e32 v84, vcc, s1, v48
	v_add_u32_e32 v32, s70, v32
	s_nop 0
	v_addc_co_u32_e32 v85, vcc, 0, v49, vcc
	s_waitcnt vmcnt(0)
	v_cvt_f32_f16_e32 v86, v68
	v_cvt_f32_f16_sdwa v87, v68 dst_sel:DWORD dst_unused:UNUSED_PAD src0_sel:WORD_1
	v_cvt_f32_f16_e32 v68, v69
	v_cvt_f32_f16_sdwa v69, v69 dst_sel:DWORD dst_unused:UNUSED_PAD src0_sel:WORD_1
	s_waitcnt lgkmcnt(0)
; DI float bf_lo(unsigned u) { return __uint_as_float(u << 16); }
; DI float bf_hi(unsigned u) { return __uint_as_float(u & 0xffff0000u); }
; DI void phase_row(const Params& P, const void* xs, int sh, void* xd, int dh, int ln, int gl, int gidx, float wgt, int modl, int shidx, bool dry = false) {
;     ...
;             const float* gate = mod + (gl * 2 + b) * 9216 + gidx * 1024;
; #pragma unroll
;             for (int j = 0; j < 4; ++j) { const f32x4 g = (*(const f32x4*)(gate + 4 * lane + 256 * j) + 1.f) * wgt;
;                 const f32x4 f = {bf_lo(fv[j].x), bf_hi(fv[j].x), bf_lo(fv[j].y), bf_hi(fv[j].y)};
;                 v[j] = v[j] * DN_ALPHA + g * f; }
;             float s = 0.f;
; #pragma unroll
;             for (int j = 0; j < 4; ++j) s += (v[j][0] + v[j][1]) + (v[j][2] + v[j][3]);
;             const float mean = wave_sum(s, lane) * (1.f / 1024.f);
;             float q = 0.f;
; #pragma unroll
;             for (int j = 0; j < 4; ++j) { v[j] = v[j] - mean; q += (v[j][0] * v[j][0] + v[j][1] * v[j][1]) + (v[j][2] * v[j][2] + v[j][3] * v[j][3]); }
	v_pk_add_f32 v[54:55], v[54:55], 1.0 op_sel_hi:[1,0]
	v_pk_add_f32 v[52:53], v[52:53], 1.0 op_sel_hi:[1,0]
	v_cvt_f32_f16_e32 v88, v70
	v_cvt_f32_f16_sdwa v89, v70 dst_sel:DWORD dst_unused:UNUSED_PAD src0_sel:WORD_1
	v_cvt_f32_f16_e32 v70, v71
	v_cvt_f32_f16_sdwa v71, v71 dst_sel:DWORD dst_unused:UNUSED_PAD src0_sel:WORD_1
	v_pk_add_f32 v[58:59], v[58:59], 1.0 op_sel_hi:[1,0]
	v_pk_add_f32 v[56:57], v[56:57], 1.0 op_sel_hi:[1,0]
	v_cvt_f32_f16_e32 v90, v72
	v_cvt_f32_f16_sdwa v91, v72 dst_sel:DWORD dst_unused:UNUSED_PAD src0_sel:WORD_1
	v_cvt_f32_f16_e32 v72, v73
	v_cvt_f32_f16_sdwa v73, v73 dst_sel:DWORD dst_unused:UNUSED_PAD src0_sel:WORD_1
	v_lshlrev_b32_e32 v94, 16, v76
	v_and_b32_e32 v95, 0xffff0000, v76
	v_lshlrev_b32_e32 v76, 16, v77
	v_and_b32_e32 v77, 0xffff0000, v77
	v_pk_mul_f32 v[54:55], v[54:55], 0.5 op_sel_hi:[1,0]
	v_pk_mul_f32 v[52:53], v[52:53], 0.5 op_sel_hi:[1,0]
	v_pk_add_f32 v[62:63], v[62:63], 1.0 op_sel_hi:[1,0]
	v_pk_add_f32 v[60:61], v[60:61], 1.0 op_sel_hi:[1,0]
	v_cvt_f32_f16_e32 v92, v74
	v_cvt_f32_f16_sdwa v93, v74 dst_sel:DWORD dst_unused:UNUSED_PAD src0_sel:WORD_1
	v_cvt_f32_f16_e32 v74, v75
	v_cvt_f32_f16_sdwa v75, v75 dst_sel:DWORD dst_unused:UNUSED_PAD src0_sel:WORD_1
	v_lshlrev_b32_e32 v96, 16, v78
	v_and_b32_e32 v97, 0xffff0000, v78
	v_lshlrev_b32_e32 v78, 16, v79
	v_and_b32_e32 v79, 0xffff0000, v79
	v_pk_mul_f32 v[58:59], v[58:59], 0.5 op_sel_hi:[1,0]
	v_pk_mul_f32 v[56:57], v[56:57], 0.5 op_sel_hi:[1,0]
	v_pk_mul_f32 v[54:55], v[54:55], v[76:77]
	v_pk_mul_f32 v[52:53], v[52:53], v[94:95]
	v_pk_add_f32 v[66:67], v[66:67], 1.0 op_sel_hi:[1,0]
	v_pk_add_f32 v[64:65], v[64:65], 1.0 op_sel_hi:[1,0]
	v_lshlrev_b32_e32 v98, 16, v80
	v_and_b32_e32 v99, 0xffff0000, v80
	v_lshlrev_b32_e32 v80, 16, v81
	v_and_b32_e32 v81, 0xffff0000, v81
	v_pk_mul_f32 v[62:63], v[62:63], 0.5 op_sel_hi:[1,0]
	v_pk_mul_f32 v[60:61], v[60:61], 0.5 op_sel_hi:[1,0]
	v_pk_mul_f32 v[58:59], v[58:59], v[78:79]
	v_pk_mul_f32 v[56:57], v[56:57], v[96:97]
	v_pk_fma_f32 v[54:55], v[68:69], s[42:43], v[54:55] op_sel_hi:[1,0,1]
	v_pk_fma_f32 v[52:53], v[86:87], s[42:43], v[52:53] op_sel_hi:[1,0,1]
	v_lshlrev_b32_e32 v100, 16, v82
	v_and_b32_e32 v101, 0xffff0000, v82
	v_lshlrev_b32_e32 v82, 16, v83
	v_and_b32_e32 v83, 0xffff0000, v83
	v_pk_mul_f32 v[66:67], v[66:67], 0.5 op_sel_hi:[1,0]
	v_pk_mul_f32 v[64:65], v[64:65], 0.5 op_sel_hi:[1,0]
	v_pk_mul_f32 v[62:63], v[62:63], v[80:81]
	v_pk_mul_f32 v[60:61], v[60:61], v[98:99]
	v_pk_fma_f32 v[58:59], v[70:71], s[42:43], v[58:59] op_sel_hi:[1,0,1]
	v_pk_fma_f32 v[56:57], v[88:89], s[42:43], v[56:57] op_sel_hi:[1,0,1]
	v_add_f32_e32 v33, v52, v53
	v_add_f32_e32 v45, v54, v55
	v_pk_mul_f32 v[66:67], v[66:67], v[82:83]
	v_pk_mul_f32 v[64:65], v[64:65], v[100:101]
	v_pk_fma_f32 v[62:63], v[72:73], s[42:43], v[62:63] op_sel_hi:[1,0,1]
	v_pk_fma_f32 v[60:61], v[90:91], s[42:43], v[60:61] op_sel_hi:[1,0,1]
	v_add_f32_e32 v68, v56, v57
	v_add_f32_e32 v69, v58, v59
	v_add_f32_e32 v33, v33, v45
	v_pk_fma_f32 v[66:67], v[74:75], s[42:43], v[66:67] op_sel_hi:[1,0,1]
	v_pk_fma_f32 v[64:65], v[92:93], s[42:43], v[64:65] op_sel_hi:[1,0,1]
	v_add_f32_e32 v70, v60, v61
	v_add_f32_e32 v71, v62, v63
	v_add_f32_e32 v45, v68, v69
	v_add_f32_e32 v33, 0, v33
	v_add_f32_e32 v72, v64, v65
	v_add_f32_e32 v73, v66, v67
	v_add_f32_e32 v68, v70, v71
	v_add_f32_e32 v33, v33, v45
	v_add_f32_e32 v69, v72, v73
	v_add_f32_e32 v33, v33, v68
	v_add_f32_e32 v33, v33, v69
	s_nop 1
	v_add_f32_dpp v33, v33, v33 quad_perm:[1,0,3,2] row_mask:0xf bank_mask:0xf bound_ctrl:1
	s_nop 1
	v_add_f32_dpp v33, v33, v33 quad_perm:[2,3,0,1] row_mask:0xf bank_mask:0xf bound_ctrl:1
	s_nop 1
	v_add_f32_dpp v33, v33, v33 row_half_mirror row_mask:0xf bank_mask:0xf bound_ctrl:1
	s_nop 1
	v_add_f32_dpp v33, v33, v33 row_mirror row_mask:0xf bank_mask:0xf bound_ctrl:1
	v_mov_b32_e32 v45, v33
	s_nop 1
	v_permlane16_swap_b32_e32 v33, v45
	v_add_f32_e32 v33, v33, v45
	v_mov_b32_e32 v45, v33
	s_nop 1
	v_permlane32_swap_b32_e32 v33, v45
	v_add_f32_e32 v33, v33, v45
	v_fmac_f32_e32 v55, 0xba800000, v33
	v_fmac_f32_e32 v53, 0xba800000, v33
	v_fmac_f32_e32 v59, 0xba800000, v33
	v_fmac_f32_e32 v57, 0xba800000, v33
	v_fmamk_f32 v54, v33, 0xba800000, v54
	v_fmamk_f32 v52, v33, 0xba800000, v52
	v_fmamk_f32 v58, v33, 0xba800000, v58
	v_fmamk_f32 v56, v33, 0xba800000, v56
	v_fmamk_f32 v62, v33, 0xba800000, v62
	v_fmac_f32_e32 v63, 0xba800000, v33
	v_fmamk_f32 v60, v33, 0xba800000, v60
	v_fmac_f32_e32 v61, 0xba800000, v33
	v_fmamk_f32 v66, v33, 0xba800000, v66
	v_fmac_f32_e32 v67, 0xba800000, v33
	v_fmamk_f32 v64, v33, 0xba800000, v64
	v_fmac_f32_e32 v65, 0xba800000, v33
	v_mul_f32_e32 v33, v53, v53
	v_mul_f32_e32 v45, v55, v55
	v_mul_f32_e32 v68, v57, v57
	v_mul_f32_e32 v69, v59, v59
; DI unsigned pk_bf16(float lo, float hi) { unsigned r; asm("v_cvt_pk_bf16_f32 %0, %1, %2" : "=v"(r) : "v"(lo), "v"(hi)); return r; }
; DI void phase_row(const Params& P, const void* xs, int sh, void* xd, int dh, int ln, int gl, int gidx, float wgt, int modl, int shidx, bool dry = false) {
;     ...
;             for (int j = 0; j < 4; ++j) { v[j] = v[j] - mean; q += (v[j][0] * v[j][0] + v[j][1] * v[j][1]) + (v[j][2] * v[j][2] + v[j][3] * v[j][3]); }
;             const float rstd = rsqrtf(wave_sum(q, lane) * (1.f / 1024.f) + LN_EPS);
; #pragma unroll
;             for (int j = 0; j < 4; ++j) { const f32x4 g = *(const f32x4*)(P.ln_g + ln * D + 4 * lane + 256 * j), bb = *(const f32x4*)(P.ln_b + ln * D + 4 * lane + 256 * j); v[j] = v[j] * rstd * g + bb; }
;             if (dry) { if (v[0][0] + v[1][1] + v[2][2] + v[3][3] == 12345.678f) P.xbuf[row] = 0.f; continue; }
; #pragma unroll
;             for (int j = 0; j < 4; ++j) { const size_t e = (size_t)row * D + 4 * lane + 256 * j;
;                 if (dh) __builtin_nontemporal_store(f4_to_h4(v[j]), (u32x2*)((unsigned short*)xd + e)); else __builtin_nontemporal_store(v[j], (f32x4*)((float*)xd + e)); }
;         }
;         if (modl >= 0) {
;             const float* shp = mod + (modl * 2 + b) * 9216 + shidx * 1024; const float* sc = shp + 1024;
; #pragma unroll
;             for (int j = 0; j < 4; ++j) { const f32x4 s4 = *(const f32x4*)(shp + 4 * lane + 256 * j), c4 = *(const f32x4*)(sc + 4 * lane + 256 * j);
;                 const f32x4 u = v[j] * (c4 + 1.f) + s4; u32x2 o; o.x = pk_bf16(u[0], u[1]); o.y = pk_bf16(u[2], u[3]);
;                 *(u32x2*)(U + (size_t)row * D + 4 * lane + 256 * j) = o; }
	v_mul_f32_e32 v70, v61, v61
	v_mul_f32_e32 v71, v63, v63
	v_fmac_f32_e32 v33, v52, v52
	v_fmac_f32_e32 v45, v54, v54
	v_fmac_f32_e32 v68, v56, v56
	v_fmac_f32_e32 v69, v58, v58
	v_mul_f32_e32 v72, v65, v65
	v_mul_f32_e32 v73, v67, v67
	v_fmac_f32_e32 v70, v60, v60
	v_fmac_f32_e32 v71, v62, v62
	v_add_f32_e32 v33, v33, v45
	v_add_f32_e32 v45, v68, v69
	v_fmac_f32_e32 v72, v64, v64
	v_fmac_f32_e32 v73, v66, v66
	v_add_f32_e32 v68, v70, v71
	v_add_f32_e32 v33, v33, v45
	v_add_f32_e32 v69, v72, v73
	v_add_f32_e32 v33, v68, v33
	v_add_f32_e32 v33, v69, v33
	s_nop 1
	v_add_f32_dpp v33, v33, v33 quad_perm:[1,0,3,2] row_mask:0xf bank_mask:0xf bound_ctrl:1
	s_nop 1
	v_add_f32_dpp v33, v33, v33 quad_perm:[2,3,0,1] row_mask:0xf bank_mask:0xf bound_ctrl:1
	s_nop 1
	v_add_f32_dpp v33, v33, v33 row_half_mirror row_mask:0xf bank_mask:0xf bound_ctrl:1
	s_nop 1
	v_add_f32_dpp v33, v33, v33 row_mirror row_mask:0xf bank_mask:0xf bound_ctrl:1
	v_mov_b32_e32 v45, v33
	s_nop 1
	v_permlane16_swap_b32_e32 v33, v45
	v_add_f32_e32 v33, v33, v45
	v_mov_b32_e32 v45, v33
	s_nop 1
	v_permlane32_swap_b32_e32 v33, v45
	v_add_f32_e32 v33, v33, v45
	v_fmamk_f32 v33, v33, 0x3a800000, v198
	v_mul_f32_e32 v45, 0x4b800000, v33
	v_cmp_gt_f32_e32 vcc, s25, v33
	s_nop 1
	v_cndmask_b32_e32 v33, v33, v45, vcc
	v_rsq_f32_e32 v33, v33
	s_nop 0
	v_mul_f32_e32 v45, 0x45800000, v33
	v_cndmask_b32_e32 v68, v33, v45, vcc
	v_pk_mul_f32 v[54:55], v[54:55], v[68:69] op_sel_hi:[1,0]
	v_pk_mul_f32 v[52:53], v[52:53], v[68:69] op_sel_hi:[1,0]
	v_pk_mul_f32 v[56:57], v[56:57], v[68:69] op_sel_hi:[1,0]
	v_pk_mul_f32 v[58:59], v[58:59], v[68:69] op_sel_hi:[1,0]
	v_pk_mul_f32 v[60:61], v[60:61], v[68:69] op_sel_hi:[1,0]
	v_pk_mul_f32 v[62:63], v[62:63], v[68:69] op_sel_hi:[1,0]
	v_pk_mul_f32 v[64:65], v[64:65], v[68:69] op_sel_hi:[1,0]
	v_pk_mul_f32 v[66:67], v[66:67], v[68:69] op_sel_hi:[1,0]
	v_pk_fma_f32 v[8:9], v[112:113], v[52:53], v[128:129]
	v_pk_fma_f32 v[10:11], v[114:115], v[54:55], v[130:131]
	v_pk_fma_f32 v[18:19], v[106:107], v[58:59], v[122:123]
	v_pk_fma_f32 v[16:17], v[104:105], v[56:57], v[120:121]
	v_pk_fma_f32 v[14:15], v[118:119], v[62:63], v[134:135]
	v_pk_fma_f32 v[12:13], v[116:117], v[60:61], v[132:133]
	v_pk_fma_f32 v[22:23], v[110:111], v[66:67], v[126:127]
	v_pk_fma_f32 v[20:21], v[108:109], v[64:65], v[124:125]
	v_cvt_pk_f16_f32 v1, v10, v11
	v_cvt_pk_f16_f32 v0, v8, v9
	v_cvt_pk_f16_f32 v3, v18, v19
	v_cvt_pk_f16_f32 v2, v16, v17
	v_cvt_pk_f16_f32 v5, v14, v15
	v_cvt_pk_f16_f32 v4, v12, v13
	v_cvt_pk_f16_f32 v7, v22, v23
	v_cvt_pk_f16_f32 v6, v20, v21
	global_store_dwordx2 v[50:51], v[0:1], off nt
	global_store_dwordx2 v[50:51], v[2:3], off offset:512 nt
	global_store_dwordx2 v[50:51], v[4:5], off offset:1024 nt
	global_store_dwordx2 v[50:51], v[6:7], off offset:1536 nt
	flat_load_dwordx4 v[0:3], v[84:85]
	s_nop 0
	flat_load_dwordx4 v[4:7], v[48:49]
	v_lshl_add_u64 v[24:25], v[48:49], 0, s[44:45]
	v_cmp_lt_i32_e32 vcc, s20, v32
	s_or_b64 s[40:41], vcc, s[40:41]
	s_waitcnt vmcnt(0) lgkmcnt(0)
	v_pk_add_f32 v[0:1], v[0:1], 1.0 op_sel_hi:[1,0]
	v_pk_add_f32 v[2:3], v[2:3], 1.0 op_sel_hi:[1,0]
	v_pk_fma_f32 v[0:1], v[8:9], v[0:1], v[4:5]
	v_pk_fma_f32 v[2:3], v[10:11], v[2:3], v[6:7]
	v_cvt_pk_bf16_f32 v0, v0, v1
	s_nop 0
	v_cvt_pk_bf16_f32 v1, v2, v3
	flat_store_dwordx2 v[46:47], v[0:1]
	flat_load_dwordx4 v[0:3], v[24:25] offset:1024
	s_nop 0
	flat_load_dwordx4 v[4:7], v[48:49] offset:1024
	s_waitcnt vmcnt(0) lgkmcnt(0)
	v_pk_add_f32 v[0:1], v[0:1], 1.0 op_sel_hi:[1,0]
	v_pk_add_f32 v[2:3], v[2:3], 1.0 op_sel_hi:[1,0]
	v_pk_fma_f32 v[0:1], v[16:17], v[0:1], v[4:5]
	v_pk_fma_f32 v[2:3], v[18:19], v[2:3], v[6:7]
	v_cvt_pk_bf16_f32 v0, v0, v1
	s_nop 0
	v_cvt_pk_bf16_f32 v1, v2, v3
	flat_store_dwordx2 v[46:47], v[0:1] offset:512
	flat_load_dwordx4 v[0:3], v[24:25] offset:2048
	s_nop 0
	flat_load_dwordx4 v[4:7], v[48:49] offset:2048
	s_waitcnt vmcnt(0) lgkmcnt(0)
	v_pk_add_f32 v[0:1], v[0:1], 1.0 op_sel_hi:[1,0]
	v_pk_add_f32 v[2:3], v[2:3], 1.0 op_sel_hi:[1,0]
	v_pk_fma_f32 v[0:1], v[12:13], v[0:1], v[4:5]
	v_pk_fma_f32 v[2:3], v[14:15], v[2:3], v[6:7]
	v_cvt_pk_bf16_f32 v0, v0, v1
	s_nop 0
	v_cvt_pk_bf16_f32 v1, v2, v3
	flat_store_dwordx2 v[46:47], v[0:1] offset:1024
	flat_load_dwordx4 v[0:3], v[24:25] offset:3072
	s_nop 0
	flat_load_dwordx4 v[4:7], v[48:49] offset:3072
	s_waitcnt vmcnt(0) lgkmcnt(0)
	v_pk_add_f32 v[0:1], v[0:1], 1.0 op_sel_hi:[1,0]
	v_pk_add_f32 v[2:3], v[2:3], 1.0 op_sel_hi:[1,0]
	v_pk_fma_f32 v[0:1], v[20:21], v[0:1], v[4:5]
	v_pk_fma_f32 v[2:3], v[22:23], v[2:3], v[6:7]
	v_cvt_pk_bf16_f32 v0, v0, v1
	s_nop 0
	v_cvt_pk_bf16_f32 v1, v2, v3
	flat_store_dwordx2 v[46:47], v[0:1] offset:1536
	s_andn2_b64 exec, exec, s[40:41]
	s_cbranch_execnz .LBB0_107

; DI float bf_lo(unsigned u) { return __uint_as_float(u << 16); }
; DI float bf_hi(unsigned u) { return __uint_as_float(u & 0xffff0000u); }
; DI int obid() { int b = blockIdx.x; asm volatile("" : "+s"(b)); return b; }
; DI f32x4 h4_to_f4(u32x2 t) { const h16x4 h = __builtin_bit_cast(h16x4, t); return (f32x4){(float)h[0], (float)h[1], (float)h[2], (float)h[3]}; }
; DI void phase_row(const Params& P, const void* xs, int sh, void* xd, int dh, int ln, int gl, int gidx, float wgt, int modl, int shidx, bool dry = false) {
;     ...
;     for (int row = obid() * 8 + w; row < T; row += gridDim.x * 8) {
;         const int b = row >= SEQ;
;         f32x4 v[4];
; #pragma unroll
;         for (int j = 0; j < 4; ++j) { const size_t e = (size_t)row * D + 4 * lane + 256 * j;
;             if (sh) v[j] = h4_to_f4(__builtin_nontemporal_load((const u32x2*)((const unsigned short*)xs + e))); else v[j] = __builtin_nontemporal_load((const f32x4*)((const float*)xs + e)); }
;         if (ln >= 0) {
;             u32x2 fv[4];
; #pragma unroll
;             for (int j = 0; j < 4; ++j) fv[j] = __builtin_nontemporal_load((const u32x2*)(U + (size_t)row * D + 4 * lane + 256 * j));
;             const float* gate = mod + (gl * 2 + b) * 9216 + gidx * 1024;
; #pragma unroll
;             for (int j = 0; j < 4; ++j) { const f32x4 g = (*(const f32x4*)(gate + 4 * lane + 256 * j) + 1.f) * wgt;
;                 const f32x4 f = {bf_lo(fv[j].x), bf_hi(fv[j].x), bf_lo(fv[j].y), bf_hi(fv[j].y)};
;                 v[j] = v[j] * DN_ALPHA + g * f; }
.LBB0_110:
	s_and_b64 vcc, exec, s[2:3]
	s_cbranch_vccz .LBB0_116
	v_readlane_b32 s2, v245, 33
	s_cmp_eq_u32 s2, 11
	s_mov_b64 s[48:49], -1
	s_cbranch_scc0 .LBB0_116
	s_waitcnt vmcnt(0)
	v_mov_b32_e32 v0, v195
	s_load_dwordx8 s[40:47], s[84:85], 0xc8
	v_ashrrev_i32_e32 v1, 6, v0
	s_mov_b32 s2, s28
	s_waitcnt lgkmcnt(0)
	s_mov_b64 s[26:27], s[46:47]
	s_mov_b64 s[30:31], s[46:47]
	s_nop 0
	v_lshl_add_u32 v32, s2, 3, v1
	v_cmp_gt_i32_e32 vcc, s75, v32
	s_and_saveexec_b64 s[2:3], vcc
	s_mov_b32 s42, 0x3fb504f3
	s_mov_b64 s[44:45], 0x1000
	s_cbranch_execz .LBB0_115
	v_lshlrev_b32_e32 v0, 2, v0
	v_and_b32_e32 v0, 0xfc, v0
	s_load_dwordx16 s[48:63], s[84:85], 0x0
	v_lshlrev_b32_e32 v184, 1, v0
	s_waitcnt lgkmcnt(0)
	s_load_dwordx8 s[48:55], s[84:85], 0xc8
	v_lshl_add_u64 v[2:3], s[30:31], 0, v[184:185]
	s_mov_b64 s[30:31], 0x5808000
	v_lshl_add_u64 v[34:35], v[2:3], 0, s[30:31]
	v_lshlrev_b32_e32 v2, 2, v0
	v_mov_b32_e32 v3, v185
	v_lshl_add_u64 v[4:5], s[26:27], 0, v[2:3]
	s_mov_b64 s[30:31], 0x5585000
	v_lshl_add_u64 v[36:37], v[4:5], 0, s[30:31]
	s_add_u32 s30, s26, 0x5586000
	v_lshl_add_u64 v[4:5], s[62:63], 0, v[2:3]
	v_lshl_add_u64 v[2:3], s[4:5], 0, v[2:3]
	s_addc_u32 s31, s27, 0
	s_mov_b64 s[60:61], 0
	v_lshl_add_u64 v[38:39], v[4:5], 0, s[44:45]
	v_lshl_add_u64 v[40:41], v[2:3], 0, s[44:45]
	s_waitcnt lgkmcnt(0)
	v_lshl_add_u64 v[42:43], s[52:53], 0, v[184:185]
	s_mov_b64 s[40:41], 0
	v_lshlrev_b32_e32 v44, 2, v0
	global_load_dwordx4 v[112:115], v[38:39], off
	global_load_dwordx4 v[104:107], v[38:39], off offset:1024
	global_load_dwordx4 v[128:131], v[40:41], off
	global_load_dwordx4 v[120:123], v[40:41], off offset:1024
	global_load_dwordx4 v[116:119], v[38:39], off offset:2048
	global_load_dwordx4 v[108:111], v[38:39], off offset:3072
	global_load_dwordx4 v[132:135], v[40:41], off offset:2048
	global_load_dwordx4 v[124:127], v[40:41], off offset:3072
	v_mov_b32_e32 v184, 0
	v_lshl_add_u64 v[102:103], v[36:37], 0, v[184:185]
	flat_load_dwordx4 v[136:139], v[102:103]
	flat_load_dwordx4 v[140:143], v[102:103] offset:1024
	flat_load_dwordx4 v[144:147], v[102:103] offset:2048
	flat_load_dwordx4 v[148:151], v[102:103] offset:3072
	v_mov_b32_e32 v184, v203
	v_lshl_add_u64 v[102:103], v[36:37], 0, v[184:185]
	flat_load_dwordx4 v[152:155], v[102:103]
	flat_load_dwordx4 v[156:159], v[102:103] offset:1024
	flat_load_dwordx4 v[160:163], v[102:103] offset:2048
	flat_load_dwordx4 v[164:167], v[102:103] offset:3072
	s_waitcnt vmcnt(0) lgkmcnt(0)
.LBB0_114:
	v_cmp_lt_i32_e32 vcc, s23, v32
	v_ashrrev_i32_e32 v33, 31, v32
	v_lshlrev_b64 v[48:49], 11, v[32:33]
	v_cndmask_b32_e32 v184, 0, v203, vcc
	v_mov_b32_e32 v45, v185
	v_lshl_add_u64 v[46:47], v[36:37], 0, v[184:185]
	v_lshl_add_u64 v[68:69], s[30:31], 0, v[184:185]
	v_lshl_add_u64 v[50:51], v[42:43], 0, v[48:49]
	v_cndmask_b32_e32 v52, v136, v152, vcc
	v_cndmask_b32_e32 v53, v137, v153, vcc
	v_cndmask_b32_e32 v54, v138, v154, vcc
	v_cndmask_b32_e32 v55, v139, v155, vcc
	v_cndmask_b32_e32 v56, v140, v156, vcc
	v_cndmask_b32_e32 v57, v141, v157, vcc
	v_cndmask_b32_e32 v58, v142, v158, vcc
	v_cndmask_b32_e32 v59, v143, v159, vcc
	v_cndmask_b32_e32 v60, v144, v160, vcc
	v_cndmask_b32_e32 v61, v145, v161, vcc
	v_cndmask_b32_e32 v62, v146, v162, vcc
	v_cndmask_b32_e32 v63, v147, v163, vcc
	v_cndmask_b32_e32 v64, v148, v164, vcc
	v_cndmask_b32_e32 v65, v149, v165, vcc
	v_cndmask_b32_e32 v66, v150, v166, vcc
	v_cndmask_b32_e32 v67, v151, v167, vcc
	v_lshl_add_u64 v[46:47], v[34:35], 0, v[48:49]
	v_lshl_add_u64 v[48:49], v[68:69], 0, v[44:45]
	global_load_dwordx2 v[68:69], v[50:51], off nt
	global_load_dwordx2 v[70:71], v[50:51], off offset:512 nt
	global_load_dwordx2 v[72:73], v[50:51], off offset:1024 nt
	global_load_dwordx2 v[74:75], v[50:51], off offset:1536 nt
	flat_load_dwordx2 v[76:77], v[46:47] nt
	flat_load_dwordx2 v[78:79], v[46:47] offset:512 nt
	flat_load_dwordx2 v[80:81], v[46:47] offset:1024 nt
	flat_load_dwordx2 v[82:83], v[46:47] offset:1536 nt
	v_add_co_u32_e32 v84, vcc, s1, v48
	v_add_u32_e32 v32, s70, v32
	s_nop 0
	v_addc_co_u32_e32 v85, vcc, 0, v49, vcc
	s_waitcnt vmcnt(0)
	v_cvt_f32_f16_e32 v86, v68
	v_cvt_f32_f16_sdwa v87, v68 dst_sel:DWORD dst_unused:UNUSED_PAD src0_sel:WORD_1
	v_cvt_f32_f16_e32 v68, v69
	v_cvt_f32_f16_sdwa v69, v69 dst_sel:DWORD dst_unused:UNUSED_PAD src0_sel:WORD_1
	v_cvt_f32_f16_e32 v88, v70
	v_cvt_f32_f16_sdwa v89, v70 dst_sel:DWORD dst_unused:UNUSED_PAD src0_sel:WORD_1
	v_cvt_f32_f16_e32 v70, v71
	v_cvt_f32_f16_sdwa v71, v71 dst_sel:DWORD dst_unused:UNUSED_PAD src0_sel:WORD_1
	s_waitcnt lgkmcnt(0)
; DI float bf_lo(unsigned u) { return __uint_as_float(u << 16); }
; DI float bf_hi(unsigned u) { return __uint_as_float(u & 0xffff0000u); }
; DI void phase_row(const Params& P, const void* xs, int sh, void* xd, int dh, int ln, int gl, int gidx, float wgt, int modl, int shidx, bool dry = false) {
;     ...
;             for (int j = 0; j < 4; ++j) { const f32x4 g = (*(const f32x4*)(gate + 4 * lane + 256 * j) + 1.f) * wgt;
;                 const f32x4 f = {bf_lo(fv[j].x), bf_hi(fv[j].x), bf_lo(fv[j].y), bf_hi(fv[j].y)};
;                 v[j] = v[j] * DN_ALPHA + g * f; }
;             float s = 0.f;
; #pragma unroll
;             for (int j = 0; j < 4; ++j) s += (v[j][0] + v[j][1]) + (v[j][2] + v[j][3]);
;             const float mean = wave_sum(s, lane) * (1.f / 1024.f);
;             float q = 0.f;
; #pragma unroll
;             for (int j = 0; j < 4; ++j) { v[j] = v[j] - mean; q += (v[j][0] * v[j][0] + v[j][1] * v[j][1]) + (v[j][2] * v[j][2] + v[j][3] * v[j][3]); }
;             const float rstd = rsqrtf(wave_sum(q, lane) * (1.f / 1024.f) + LN_EPS);
	v_pk_add_f32 v[54:55], v[54:55], 1.0 op_sel_hi:[1,0]
	v_pk_add_f32 v[52:53], v[52:53], 1.0 op_sel_hi:[1,0]
	v_cvt_f32_f16_e32 v90, v72
	v_cvt_f32_f16_sdwa v91, v72 dst_sel:DWORD dst_unused:UNUSED_PAD src0_sel:WORD_1
	v_cvt_f32_f16_e32 v72, v73
	v_cvt_f32_f16_sdwa v73, v73 dst_sel:DWORD dst_unused:UNUSED_PAD src0_sel:WORD_1
	v_lshlrev_b32_e32 v94, 16, v76
	v_and_b32_e32 v95, 0xffff0000, v76
	v_lshlrev_b32_e32 v76, 16, v77
	v_and_b32_e32 v77, 0xffff0000, v77
	v_pk_add_f32 v[58:59], v[58:59], 1.0 op_sel_hi:[1,0]
	v_pk_add_f32 v[56:57], v[56:57], 1.0 op_sel_hi:[1,0]
	v_cvt_f32_f16_e32 v92, v74
	v_cvt_f32_f16_sdwa v93, v74 dst_sel:DWORD dst_unused:UNUSED_PAD src0_sel:WORD_1
	v_cvt_f32_f16_e32 v74, v75
	v_cvt_f32_f16_sdwa v75, v75 dst_sel:DWORD dst_unused:UNUSED_PAD src0_sel:WORD_1
	v_lshlrev_b32_e32 v96, 16, v78
	v_and_b32_e32 v97, 0xffff0000, v78
	v_lshlrev_b32_e32 v78, 16, v79
	v_and_b32_e32 v79, 0xffff0000, v79
	v_pk_mul_f32 v[54:55], v[54:55], v[76:77]
	v_pk_mul_f32 v[52:53], v[52:53], v[94:95]
	v_pk_add_f32 v[62:63], v[62:63], 1.0 op_sel_hi:[1,0]
	v_pk_add_f32 v[60:61], v[60:61], 1.0 op_sel_hi:[1,0]
	v_lshlrev_b32_e32 v98, 16, v80
	v_and_b32_e32 v99, 0xffff0000, v80
	v_lshlrev_b32_e32 v80, 16, v81
	v_and_b32_e32 v81, 0xffff0000, v81
	v_pk_mul_f32 v[58:59], v[58:59], v[78:79]
	v_pk_mul_f32 v[56:57], v[56:57], v[96:97]
	v_pk_fma_f32 v[54:55], v[68:69], s[42:43], v[54:55] op_sel_hi:[1,0,1]
	v_pk_fma_f32 v[52:53], v[86:87], s[42:43], v[52:53] op_sel_hi:[1,0,1]
	v_pk_add_f32 v[66:67], v[66:67], 1.0 op_sel_hi:[1,0]
	v_pk_add_f32 v[64:65], v[64:65], 1.0 op_sel_hi:[1,0]
	v_lshlrev_b32_e32 v100, 16, v82
	v_and_b32_e32 v101, 0xffff0000, v82
	v_lshlrev_b32_e32 v82, 16, v83
	v_and_b32_e32 v83, 0xffff0000, v83
	v_pk_mul_f32 v[62:63], v[62:63], v[80:81]
	v_pk_mul_f32 v[60:61], v[60:61], v[98:99]
	v_pk_fma_f32 v[58:59], v[70:71], s[42:43], v[58:59] op_sel_hi:[1,0,1]
	v_pk_fma_f32 v[56:57], v[88:89], s[42:43], v[56:57] op_sel_hi:[1,0,1]
	v_add_f32_e32 v33, v52, v53
	v_add_f32_e32 v45, v54, v55
	v_pk_mul_f32 v[66:67], v[66:67], v[82:83]
	v_pk_mul_f32 v[64:65], v[64:65], v[100:101]
	v_pk_fma_f32 v[62:63], v[72:73], s[42:43], v[62:63] op_sel_hi:[1,0,1]
	v_pk_fma_f32 v[60:61], v[90:91], s[42:43], v[60:61] op_sel_hi:[1,0,1]
	v_add_f32_e32 v68, v56, v57
	v_add_f32_e32 v69, v58, v59
	v_add_f32_e32 v33, v33, v45
	v_pk_fma_f32 v[66:67], v[74:75], s[42:43], v[66:67] op_sel_hi:[1,0,1]
	v_pk_fma_f32 v[64:65], v[92:93], s[42:43], v[64:65] op_sel_hi:[1,0,1]
	v_add_f32_e32 v70, v60, v61
	v_add_f32_e32 v71, v62, v63
	v_add_f32_e32 v45, v68, v69
	v_add_f32_e32 v33, 0, v33
	v_add_f32_e32 v72, v64, v65
	v_add_f32_e32 v73, v66, v67
	v_add_f32_e32 v68, v70, v71
	v_add_f32_e32 v33, v33, v45
	v_add_f32_e32 v69, v72, v73
	v_add_f32_e32 v33, v33, v68
	v_add_f32_e32 v33, v33, v69
	s_nop 1
	v_add_f32_dpp v33, v33, v33 quad_perm:[1,0,3,2] row_mask:0xf bank_mask:0xf bound_ctrl:1
	s_nop 1
	v_add_f32_dpp v33, v33, v33 quad_perm:[2,3,0,1] row_mask:0xf bank_mask:0xf bound_ctrl:1
	s_nop 1
	v_add_f32_dpp v33, v33, v33 row_half_mirror row_mask:0xf bank_mask:0xf bound_ctrl:1
	s_nop 1
	v_add_f32_dpp v33, v33, v33 row_mirror row_mask:0xf bank_mask:0xf bound_ctrl:1
	v_mov_b32_e32 v45, v33
	s_nop 1
	v_permlane16_swap_b32_e32 v33, v45
	v_add_f32_e32 v33, v33, v45
	v_mov_b32_e32 v45, v33
	s_nop 1
	v_permlane32_swap_b32_e32 v33, v45
	v_add_f32_e32 v33, v33, v45
	v_fmac_f32_e32 v55, 0xba800000, v33
	v_fmac_f32_e32 v53, 0xba800000, v33
	v_fmac_f32_e32 v59, 0xba800000, v33
	v_fmac_f32_e32 v57, 0xba800000, v33
	v_fmamk_f32 v54, v33, 0xba800000, v54
	v_fmamk_f32 v52, v33, 0xba800000, v52
	v_fmamk_f32 v58, v33, 0xba800000, v58
	v_fmamk_f32 v56, v33, 0xba800000, v56
	v_fmamk_f32 v62, v33, 0xba800000, v62
	v_fmac_f32_e32 v63, 0xba800000, v33
	v_fmamk_f32 v60, v33, 0xba800000, v60
	v_fmac_f32_e32 v61, 0xba800000, v33
	v_fmamk_f32 v66, v33, 0xba800000, v66
	v_fmac_f32_e32 v67, 0xba800000, v33
	v_fmamk_f32 v64, v33, 0xba800000, v64
	v_fmac_f32_e32 v65, 0xba800000, v33
	v_mul_f32_e32 v33, v53, v53
	v_mul_f32_e32 v45, v55, v55
	v_mul_f32_e32 v68, v57, v57
	v_mul_f32_e32 v69, v59, v59
	v_mul_f32_e32 v70, v61, v61
	v_mul_f32_e32 v71, v63, v63
	v_fmac_f32_e32 v33, v52, v52
	v_fmac_f32_e32 v45, v54, v54
	v_fmac_f32_e32 v68, v56, v56
	v_fmac_f32_e32 v69, v58, v58
	v_mul_f32_e32 v72, v65, v65
	v_mul_f32_e32 v73, v67, v67
	v_fmac_f32_e32 v70, v60, v60
	v_fmac_f32_e32 v71, v62, v62
	v_add_f32_e32 v33, v33, v45
; DI unsigned pk_bf16(float lo, float hi) { unsigned r; asm("v_cvt_pk_bf16_f32 %0, %1, %2" : "=v"(r) : "v"(lo), "v"(hi)); return r; }
; DI void phase_row(const Params& P, const void* xs, int sh, void* xd, int dh, int ln, int gl, int gidx, float wgt, int modl, int shidx, bool dry = false) {
;     ...
;             float q = 0.f;
; #pragma unroll
;             for (int j = 0; j < 4; ++j) { v[j] = v[j] - mean; q += (v[j][0] * v[j][0] + v[j][1] * v[j][1]) + (v[j][2] * v[j][2] + v[j][3] * v[j][3]); }
;             const float rstd = rsqrtf(wave_sum(q, lane) * (1.f / 1024.f) + LN_EPS);
; #pragma unroll
;             for (int j = 0; j < 4; ++j) { const f32x4 g = *(const f32x4*)(P.ln_g + ln * D + 4 * lane + 256 * j), bb = *(const f32x4*)(P.ln_b + ln * D + 4 * lane + 256 * j); v[j] = v[j] * rstd * g + bb; }
;             if (dry) { if (v[0][0] + v[1][1] + v[2][2] + v[3][3] == 12345.678f) P.xbuf[row] = 0.f; continue; }
; #pragma unroll
;             for (int j = 0; j < 4; ++j) { const size_t e = (size_t)row * D + 4 * lane + 256 * j;
;                 if (dh) __builtin_nontemporal_store(f4_to_h4(v[j]), (u32x2*)((unsigned short*)xd + e)); else __builtin_nontemporal_store(v[j], (f32x4*)((float*)xd + e)); }
;         }
;         if (modl >= 0) {
;             const float* shp = mod + (modl * 2 + b) * 9216 + shidx * 1024; const float* sc = shp + 1024;
; #pragma unroll
;             for (int j = 0; j < 4; ++j) { const f32x4 s4 = *(const f32x4*)(shp + 4 * lane + 256 * j), c4 = *(const f32x4*)(sc + 4 * lane + 256 * j);
;                 const f32x4 u = v[j] * (c4 + 1.f) + s4; u32x2 o; o.x = pk_bf16(u[0], u[1]); o.y = pk_bf16(u[2], u[3]);
;                 *(u32x2*)(U + (size_t)row * D + 4 * lane + 256 * j) = o; }
	v_add_f32_e32 v45, v68, v69
	v_fmac_f32_e32 v72, v64, v64
	v_fmac_f32_e32 v73, v66, v66
	v_add_f32_e32 v68, v70, v71
	v_add_f32_e32 v33, v33, v45
	v_add_f32_e32 v69, v72, v73
	v_add_f32_e32 v33, v68, v33
	v_add_f32_e32 v33, v69, v33
	s_nop 1
	v_add_f32_dpp v33, v33, v33 quad_perm:[1,0,3,2] row_mask:0xf bank_mask:0xf bound_ctrl:1
	s_nop 1
	v_add_f32_dpp v33, v33, v33 quad_perm:[2,3,0,1] row_mask:0xf bank_mask:0xf bound_ctrl:1
	s_nop 1
	v_add_f32_dpp v33, v33, v33 row_half_mirror row_mask:0xf bank_mask:0xf bound_ctrl:1
	s_nop 1
	v_add_f32_dpp v33, v33, v33 row_mirror row_mask:0xf bank_mask:0xf bound_ctrl:1
	v_mov_b32_e32 v45, v33
	s_nop 1
	v_permlane16_swap_b32_e32 v33, v45
	v_add_f32_e32 v33, v33, v45
	v_mov_b32_e32 v45, v33
	s_nop 1
	v_permlane32_swap_b32_e32 v33, v45
	v_add_f32_e32 v33, v33, v45
	v_fmamk_f32 v33, v33, 0x3a800000, v198
	v_mul_f32_e32 v45, 0x4b800000, v33
	v_cmp_gt_f32_e32 vcc, s25, v33
	s_nop 1
	v_cndmask_b32_e32 v33, v33, v45, vcc
	v_rsq_f32_e32 v33, v33
	s_nop 0
	v_mul_f32_e32 v45, 0x45800000, v33
	v_cndmask_b32_e32 v68, v33, v45, vcc
	v_pk_mul_f32 v[54:55], v[54:55], v[68:69] op_sel_hi:[1,0]
	v_pk_mul_f32 v[52:53], v[52:53], v[68:69] op_sel_hi:[1,0]
	v_pk_mul_f32 v[56:57], v[56:57], v[68:69] op_sel_hi:[1,0]
	v_pk_mul_f32 v[58:59], v[58:59], v[68:69] op_sel_hi:[1,0]
	v_pk_mul_f32 v[60:61], v[60:61], v[68:69] op_sel_hi:[1,0]
	v_pk_mul_f32 v[62:63], v[62:63], v[68:69] op_sel_hi:[1,0]
	v_pk_mul_f32 v[64:65], v[64:65], v[68:69] op_sel_hi:[1,0]
	v_pk_mul_f32 v[66:67], v[66:67], v[68:69] op_sel_hi:[1,0]
	v_pk_fma_f32 v[8:9], v[112:113], v[52:53], v[128:129]
	v_pk_fma_f32 v[10:11], v[114:115], v[54:55], v[130:131]
	v_pk_fma_f32 v[18:19], v[106:107], v[58:59], v[122:123]
	v_pk_fma_f32 v[16:17], v[104:105], v[56:57], v[120:121]
	v_pk_fma_f32 v[14:15], v[118:119], v[62:63], v[134:135]
	v_pk_fma_f32 v[12:13], v[116:117], v[60:61], v[132:133]
	v_pk_fma_f32 v[22:23], v[110:111], v[66:67], v[126:127]
	v_pk_fma_f32 v[20:21], v[108:109], v[64:65], v[124:125]
	v_cvt_pk_f16_f32 v1, v10, v11
	v_cvt_pk_f16_f32 v0, v8, v9
	v_cvt_pk_f16_f32 v3, v18, v19
	v_cvt_pk_f16_f32 v2, v16, v17
	v_cvt_pk_f16_f32 v5, v14, v15
	v_cvt_pk_f16_f32 v4, v12, v13
	v_cvt_pk_f16_f32 v7, v22, v23
	v_cvt_pk_f16_f32 v6, v20, v21
	global_store_dwordx2 v[50:51], v[0:1], off nt
	global_store_dwordx2 v[50:51], v[2:3], off offset:512 nt
	global_store_dwordx2 v[50:51], v[4:5], off offset:1024 nt
	global_store_dwordx2 v[50:51], v[6:7], off offset:1536 nt
	flat_load_dwordx4 v[0:3], v[84:85]
	s_nop 0
	flat_load_dwordx4 v[4:7], v[48:49]
	v_lshl_add_u64 v[24:25], v[48:49], 0, s[44:45]
	v_cmp_lt_i32_e32 vcc, s20, v32
	s_or_b64 s[40:41], vcc, s[40:41]
	s_waitcnt vmcnt(0) lgkmcnt(0)
	v_pk_add_f32 v[0:1], v[0:1], 1.0 op_sel_hi:[1,0]
	v_pk_add_f32 v[2:3], v[2:3], 1.0 op_sel_hi:[1,0]
	v_pk_fma_f32 v[0:1], v[8:9], v[0:1], v[4:5]
	v_pk_fma_f32 v[2:3], v[10:11], v[2:3], v[6:7]
	v_cvt_pk_bf16_f32 v0, v0, v1
	s_nop 0
	v_cvt_pk_bf16_f32 v1, v2, v3
	flat_store_dwordx2 v[46:47], v[0:1]
	flat_load_dwordx4 v[0:3], v[24:25] offset:1024
	s_nop 0
	flat_load_dwordx4 v[4:7], v[48:49] offset:1024
	s_waitcnt vmcnt(0) lgkmcnt(0)
	v_pk_add_f32 v[0:1], v[0:1], 1.0 op_sel_hi:[1,0]
	v_pk_add_f32 v[2:3], v[2:3], 1.0 op_sel_hi:[1,0]
	v_pk_fma_f32 v[0:1], v[16:17], v[0:1], v[4:5]
	v_pk_fma_f32 v[2:3], v[18:19], v[2:3], v[6:7]
	v_cvt_pk_bf16_f32 v0, v0, v1
	s_nop 0
	v_cvt_pk_bf16_f32 v1, v2, v3
	flat_store_dwordx2 v[46:47], v[0:1] offset:512
	flat_load_dwordx4 v[0:3], v[24:25] offset:2048
	s_nop 0
	flat_load_dwordx4 v[4:7], v[48:49] offset:2048
	s_waitcnt vmcnt(0) lgkmcnt(0)
	v_pk_add_f32 v[0:1], v[0:1], 1.0 op_sel_hi:[1,0]
	v_pk_add_f32 v[2:3], v[2:3], 1.0 op_sel_hi:[1,0]
	v_pk_fma_f32 v[0:1], v[12:13], v[0:1], v[4:5]
	v_pk_fma_f32 v[2:3], v[14:15], v[2:3], v[6:7]
	v_cvt_pk_bf16_f32 v0, v0, v1
	s_nop 0
	v_cvt_pk_bf16_f32 v1, v2, v3
	flat_store_dwordx2 v[46:47], v[0:1] offset:1024
	flat_load_dwordx4 v[0:3], v[24:25] offset:3072
	s_nop 0
	flat_load_dwordx4 v[4:7], v[48:49] offset:3072
	s_waitcnt vmcnt(0) lgkmcnt(0)
	v_pk_add_f32 v[0:1], v[0:1], 1.0 op_sel_hi:[1,0]
	v_pk_add_f32 v[2:3], v[2:3], 1.0 op_sel_hi:[1,0]
	v_pk_fma_f32 v[0:1], v[20:21], v[0:1], v[4:5]
	v_pk_fma_f32 v[2:3], v[22:23], v[2:3], v[6:7]
	v_cvt_pk_bf16_f32 v0, v0, v1
	s_nop 0
	v_cvt_pk_bf16_f32 v1, v2, v3
	flat_store_dwordx2 v[46:47], v[0:1] offset:1536
	s_andn2_b64 exec, exec, s[40:41]
	s_cbranch_execnz .LBB0_114

; DI float bf_lo(unsigned u) { return __uint_as_float(u << 16); }
; DI float bf_hi(unsigned u) { return __uint_as_float(u & 0xffff0000u); }
; DI int obid() { int b = blockIdx.x; asm volatile("" : "+s"(b)); return b; }
; DI f32x4 h4_to_f4(u32x2 t) { const h16x4 h = __builtin_bit_cast(h16x4, t); return (f32x4){(float)h[0], (float)h[1], (float)h[2], (float)h[3]}; }
; DI void phase_row(const Params& P, const void* xs, int sh, void* xd, int dh, int ln, int gl, int gidx, float wgt, int modl, int shidx, bool dry = false) {
;     ...
;     for (int row = obid() * 8 + w; row < T; row += gridDim.x * 8) {
;         const int b = row >= SEQ;
;         f32x4 v[4];
; #pragma unroll
;         for (int j = 0; j < 4; ++j) { const size_t e = (size_t)row * D + 4 * lane + 256 * j;
;             if (sh) v[j] = h4_to_f4(__builtin_nontemporal_load((const u32x2*)((const unsigned short*)xs + e))); else v[j] = __builtin_nontemporal_load((const f32x4*)((const float*)xs + e)); }
;         if (ln >= 0) {
;             u32x2 fv[4];
; #pragma unroll
;             for (int j = 0; j < 4; ++j) fv[j] = __builtin_nontemporal_load((const u32x2*)(U + (size_t)row * D + 4 * lane + 256 * j));
;             const float* gate = mod + (gl * 2 + b) * 9216 + gidx * 1024;
; #pragma unroll
;             for (int j = 0; j < 4; ++j) { const f32x4 g = (*(const f32x4*)(gate + 4 * lane + 256 * j) + 1.f) * wgt;
;                 const f32x4 f = {bf_lo(fv[j].x), bf_hi(fv[j].x), bf_lo(fv[j].y), bf_hi(fv[j].y)};
;                 v[j] = v[j] * DN_ALPHA + g * f; }
.LBB0_227:
	s_mov_b64 s[60:61], 0
	s_and_b64 vcc, exec, s[2:3]
	s_cbranch_vccz .LBB0_239
	v_readlane_b32 s8, v245, 33
	s_cmp_gt_i32 s8, 0
	s_cbranch_scc0 .LBB0_248
	s_cmp_gt_i32 s8, 3
	s_mov_b64 s[2:3], -1
	s_cbranch_scc0 .LBB0_236
	v_readlane_b32 s2, v245, 33
	s_cmp_eq_u32 s2, 4
	s_mov_b64 s[48:49], -1
	s_cbranch_scc0 .LBB0_235
	s_waitcnt vmcnt(0)
	v_mov_b32_e32 v0, v195
	s_load_dwordx8 s[52:59], s[84:85], 0xc8
	v_ashrrev_i32_e32 v1, 6, v0
	s_mov_b32 s2, s28
	s_waitcnt lgkmcnt(0)
	s_mov_b64 s[8:9], s[58:59]
	s_mov_b64 s[10:11], s[58:59]
	s_nop 0
	v_lshl_add_u32 v32, s2, 3, v1
	v_cmp_gt_i32_e32 vcc, s75, v32
	s_and_saveexec_b64 s[2:3], vcc
	s_load_dwordx16 s[40:55], s[84:85], 0x0
	s_mov_b32 s18, 0x3fb504f3
	s_mov_b64 s[26:27], 0x1000
	s_cbranch_execz .LBB0_234
	v_lshlrev_b32_e32 v0, 2, v0
	v_and_b32_e32 v34, 0xfc, v0
	v_lshlrev_b32_e32 v184, 1, v34
	v_lshl_add_u64 v[0:1], s[10:11], 0, v[184:185]
	s_mov_b64 s[10:11], 0x5808000
	v_lshlrev_b32_e32 v184, 2, v34
	v_lshl_add_u64 v[36:37], v[0:1], 0, s[10:11]
	v_lshl_add_u64 v[0:1], s[8:9], 0, v[184:185]
	s_mov_b64 s[10:11], 0x5582000
	s_add_u32 s8, s8, 0x5583000
	v_lshl_add_u64 v[38:39], v[0:1], 0, s[10:11]
	s_addc_u32 s9, s9, 0
	s_waitcnt lgkmcnt(0)
	v_lshl_add_u64 v[40:41], s[54:55], 0, v[184:185]
	v_lshl_add_u64 v[42:43], s[4:5], 0, v[184:185]
	s_mov_b64 s[4:5], 0
	global_load_dwordx4 v[108:111], v[40:41], off
	global_load_dwordx4 v[100:103], v[40:41], off offset:1024
	global_load_dwordx4 v[124:127], v[42:43], off
	global_load_dwordx4 v[116:119], v[42:43], off offset:1024
	global_load_dwordx4 v[112:115], v[40:41], off offset:2048
	global_load_dwordx4 v[104:107], v[40:41], off offset:3072
	global_load_dwordx4 v[128:131], v[42:43], off offset:2048
	global_load_dwordx4 v[120:123], v[42:43], off offset:3072
	v_mov_b32_e32 v184, 0
	v_lshl_add_u64 v[164:165], v[38:39], 0, v[184:185]
	flat_load_dwordx4 v[132:135], v[164:165]
	flat_load_dwordx4 v[136:139], v[164:165] offset:1024
	flat_load_dwordx4 v[140:143], v[164:165] offset:2048
	flat_load_dwordx4 v[144:147], v[164:165] offset:3072
	v_mov_b32_e32 v184, v203
	v_lshl_add_u64 v[164:165], v[38:39], 0, v[184:185]
	flat_load_dwordx4 v[148:151], v[164:165]
	flat_load_dwordx4 v[152:155], v[164:165] offset:1024
	flat_load_dwordx4 v[156:159], v[164:165] offset:2048
	flat_load_dwordx4 v[160:163], v[164:165] offset:3072
	s_waitcnt vmcnt(0) lgkmcnt(0)
.LBB0_233:
	v_cmp_lt_i32_e32 vcc, s23, v32
	v_ashrrev_i32_e32 v33, 31, v32
	v_lshlrev_b64 v[46:47], 11, v[32:33]
	v_cndmask_b32_e32 v184, 0, v203, vcc
	v_lshl_add_u64 v[44:45], v[38:39], 0, v[184:185]
	v_lshlrev_b64 v[48:49], 10, v[32:33]
	v_cndmask_b32_e32 v50, v132, v148, vcc
	v_cndmask_b32_e32 v51, v133, v149, vcc
	v_cndmask_b32_e32 v52, v134, v150, vcc
	v_cndmask_b32_e32 v53, v135, v151, vcc
	v_cndmask_b32_e32 v54, v136, v152, vcc
	v_cndmask_b32_e32 v55, v137, v153, vcc
	v_cndmask_b32_e32 v56, v138, v154, vcc
	v_cndmask_b32_e32 v57, v139, v155, vcc
	v_cndmask_b32_e32 v58, v140, v156, vcc
	v_cndmask_b32_e32 v59, v141, v157, vcc
	v_cndmask_b32_e32 v60, v142, v158, vcc
	v_cndmask_b32_e32 v61, v143, v159, vcc
	v_cndmask_b32_e32 v62, v144, v160, vcc
	v_cndmask_b32_e32 v63, v145, v161, vcc
	v_cndmask_b32_e32 v64, v146, v162, vcc
	v_cndmask_b32_e32 v65, v147, v163, vcc
	v_lshl_add_u64 v[44:45], v[36:37], 0, v[46:47]
	v_or_b32_e32 v48, v48, v34
	flat_load_dwordx2 v[82:83], v[44:45] nt
	flat_load_dwordx2 v[84:85], v[44:45] offset:512 nt
	flat_load_dwordx2 v[86:87], v[44:45] offset:1024 nt
	flat_load_dwordx2 v[88:89], v[44:45] offset:1536 nt
	v_lshl_add_u64 v[66:67], s[8:9], 0, v[184:185]
	v_lshlrev_b32_e32 v184, 2, v34
	v_lshl_add_u64 v[78:79], v[48:49], 2, s[40:41]
	v_lshl_add_u64 v[46:47], v[66:67], 0, v[184:185]
	global_load_dwordx4 v[66:69], v[78:79], off nt
	global_load_dwordx4 v[70:73], v[78:79], off offset:1024 nt
	global_load_dwordx4 v[74:77], v[78:79], off offset:2048 nt
	s_nop 0
	global_load_dwordx4 v[78:81], v[78:79], off offset:3072 nt
	v_add_co_u32_e32 v90, vcc, s1, v46
	v_lshl_add_u64 v[48:49], v[48:49], 1, s[56:57]
	s_nop 0
	v_addc_co_u32_e32 v91, vcc, 0, v47, vcc
	v_add_u32_e32 v32, s70, v32
	s_waitcnt vmcnt(0) lgkmcnt(0)
	v_pk_add_f32 v[52:53], v[52:53], 1.0 op_sel_hi:[1,0]
	v_pk_add_f32 v[50:51], v[50:51], 1.0 op_sel_hi:[1,0]
	v_pk_add_f32 v[56:57], v[56:57], 1.0 op_sel_hi:[1,0]
	v_pk_add_f32 v[54:55], v[54:55], 1.0 op_sel_hi:[1,0]
	v_lshlrev_b32_e32 v92, 16, v82
	v_and_b32_e32 v93, 0xffff0000, v82
	v_lshlrev_b32_e32 v82, 16, v83
	v_and_b32_e32 v83, 0xffff0000, v83
	v_pk_mul_f32 v[52:53], v[52:53], 0.5 op_sel_hi:[1,0]
	v_pk_mul_f32 v[50:51], v[50:51], 0.5 op_sel_hi:[1,0]
	v_pk_add_f32 v[60:61], v[60:61], 1.0 op_sel_hi:[1,0]
	v_pk_add_f32 v[58:59], v[58:59], 1.0 op_sel_hi:[1,0]
	v_lshlrev_b32_e32 v94, 16, v84
	v_and_b32_e32 v95, 0xffff0000, v84
	v_lshlrev_b32_e32 v84, 16, v85
	v_and_b32_e32 v85, 0xffff0000, v85
	v_pk_mul_f32 v[56:57], v[56:57], 0.5 op_sel_hi:[1,0]
	v_pk_mul_f32 v[54:55], v[54:55], 0.5 op_sel_hi:[1,0]
	v_pk_mul_f32 v[52:53], v[52:53], v[82:83]
	v_pk_mul_f32 v[50:51], v[50:51], v[92:93]
	v_pk_add_f32 v[64:65], v[64:65], 1.0 op_sel_hi:[1,0]
	v_pk_add_f32 v[62:63], v[62:63], 1.0 op_sel_hi:[1,0]
	v_lshlrev_b32_e32 v96, 16, v86
	v_and_b32_e32 v97, 0xffff0000, v86
	v_lshlrev_b32_e32 v86, 16, v87
	v_and_b32_e32 v87, 0xffff0000, v87
	v_pk_mul_f32 v[60:61], v[60:61], 0.5 op_sel_hi:[1,0]
	v_pk_mul_f32 v[58:59], v[58:59], 0.5 op_sel_hi:[1,0]
	v_pk_mul_f32 v[56:57], v[56:57], v[84:85]
	v_pk_mul_f32 v[54:55], v[54:55], v[94:95]
	v_pk_fma_f32 v[52:53], v[68:69], s[18:19], v[52:53] op_sel_hi:[1,0,1]
	v_pk_fma_f32 v[50:51], v[66:67], s[18:19], v[50:51] op_sel_hi:[1,0,1]
	v_lshlrev_b32_e32 v98, 16, v88
; DI float bf_lo(unsigned u) { return __uint_as_float(u << 16); }
; DI float bf_hi(unsigned u) { return __uint_as_float(u & 0xffff0000u); }
; DI void phase_row(const Params& P, const void* xs, int sh, void* xd, int dh, int ln, int gl, int gidx, float wgt, int modl, int shidx, bool dry = false) {
;     ...
;             for (int j = 0; j < 4; ++j) { const f32x4 g = (*(const f32x4*)(gate + 4 * lane + 256 * j) + 1.f) * wgt;
;                 const f32x4 f = {bf_lo(fv[j].x), bf_hi(fv[j].x), bf_lo(fv[j].y), bf_hi(fv[j].y)};
;                 v[j] = v[j] * DN_ALPHA + g * f; }
;             float s = 0.f;
; #pragma unroll
;             for (int j = 0; j < 4; ++j) s += (v[j][0] + v[j][1]) + (v[j][2] + v[j][3]);
;             const float mean = wave_sum(s, lane) * (1.f / 1024.f);
;             float q = 0.f;
; #pragma unroll
;             for (int j = 0; j < 4; ++j) { v[j] = v[j] - mean; q += (v[j][0] * v[j][0] + v[j][1] * v[j][1]) + (v[j][2] * v[j][2] + v[j][3] * v[j][3]); }
;             const float rstd = rsqrtf(wave_sum(q, lane) * (1.f / 1024.f) + LN_EPS);
; #pragma unroll
;             for (int j = 0; j < 4; ++j) { const f32x4 g = *(const f32x4*)(P.ln_g + ln * D + 4 * lane + 256 * j), bb = *(const f32x4*)(P.ln_b + ln * D + 4 * lane + 256 * j); v[j] = v[j] * rstd * g + bb; }
;             if (dry) { if (v[0][0] + v[1][1] + v[2][2] + v[3][3] == 12345.678f) P.xbuf[row] = 0.f; continue; }
; #pragma unroll
;             for (int j = 0; j < 4; ++j) { const size_t e = (size_t)row * D + 4 * lane + 256 * j;
;                 if (dh) __builtin_nontemporal_store(f4_to_h4(v[j]), (u32x2*)((unsigned short*)xd + e)); else __builtin_nontemporal_store(v[j], (f32x4*)((float*)xd + e)); }
	v_and_b32_e32 v99, 0xffff0000, v88
	v_lshlrev_b32_e32 v88, 16, v89
	v_and_b32_e32 v89, 0xffff0000, v89
	v_pk_mul_f32 v[64:65], v[64:65], 0.5 op_sel_hi:[1,0]
	v_pk_mul_f32 v[62:63], v[62:63], 0.5 op_sel_hi:[1,0]
	v_pk_mul_f32 v[60:61], v[60:61], v[86:87]
	v_pk_mul_f32 v[58:59], v[58:59], v[96:97]
	v_pk_fma_f32 v[56:57], v[72:73], s[18:19], v[56:57] op_sel_hi:[1,0,1]
	v_pk_fma_f32 v[54:55], v[70:71], s[18:19], v[54:55] op_sel_hi:[1,0,1]
	v_add_f32_e32 v33, v50, v51
	v_add_f32_e32 v35, v52, v53
	v_pk_mul_f32 v[64:65], v[64:65], v[88:89]
	v_pk_mul_f32 v[62:63], v[62:63], v[98:99]
	v_pk_fma_f32 v[60:61], v[76:77], s[18:19], v[60:61] op_sel_hi:[1,0,1]
	v_pk_fma_f32 v[58:59], v[74:75], s[18:19], v[58:59] op_sel_hi:[1,0,1]
	v_add_f32_e32 v66, v54, v55
	v_add_f32_e32 v67, v56, v57
	v_add_f32_e32 v33, v33, v35
	v_pk_fma_f32 v[64:65], v[80:81], s[18:19], v[64:65] op_sel_hi:[1,0,1]
	v_pk_fma_f32 v[62:63], v[78:79], s[18:19], v[62:63] op_sel_hi:[1,0,1]
	v_add_f32_e32 v68, v58, v59
	v_add_f32_e32 v69, v60, v61
	v_add_f32_e32 v35, v66, v67
	v_add_f32_e32 v33, 0, v33
	v_add_f32_e32 v70, v62, v63
	v_add_f32_e32 v71, v64, v65
	v_add_f32_e32 v66, v68, v69
	v_add_f32_e32 v33, v33, v35
	v_add_f32_e32 v67, v70, v71
	v_add_f32_e32 v33, v33, v66
	v_add_f32_e32 v33, v33, v67
	s_nop 1
	v_add_f32_dpp v33, v33, v33 quad_perm:[1,0,3,2] row_mask:0xf bank_mask:0xf bound_ctrl:1
	s_nop 1
	v_add_f32_dpp v33, v33, v33 quad_perm:[2,3,0,1] row_mask:0xf bank_mask:0xf bound_ctrl:1
	s_nop 1
	v_add_f32_dpp v33, v33, v33 row_half_mirror row_mask:0xf bank_mask:0xf bound_ctrl:1
	s_nop 1
	v_add_f32_dpp v33, v33, v33 row_mirror row_mask:0xf bank_mask:0xf bound_ctrl:1
	v_mov_b32_e32 v35, v33
	s_nop 1
	v_permlane16_swap_b32_e32 v33, v35
	v_add_f32_e32 v33, v33, v35
	v_mov_b32_e32 v35, v33
	s_nop 1
	v_permlane32_swap_b32_e32 v33, v35
	v_add_f32_e32 v33, v33, v35
	v_fmac_f32_e32 v53, 0xba800000, v33
	v_fmac_f32_e32 v51, 0xba800000, v33
	v_fmac_f32_e32 v57, 0xba800000, v33
	v_fmac_f32_e32 v55, 0xba800000, v33
	v_fmamk_f32 v52, v33, 0xba800000, v52
	v_fmamk_f32 v50, v33, 0xba800000, v50
	v_fmamk_f32 v56, v33, 0xba800000, v56
	v_fmamk_f32 v54, v33, 0xba800000, v54
	v_fmamk_f32 v60, v33, 0xba800000, v60
	v_fmac_f32_e32 v61, 0xba800000, v33
	v_fmamk_f32 v58, v33, 0xba800000, v58
	v_fmac_f32_e32 v59, 0xba800000, v33
	v_fmamk_f32 v64, v33, 0xba800000, v64
	v_fmac_f32_e32 v65, 0xba800000, v33
	v_fmamk_f32 v62, v33, 0xba800000, v62
	v_fmac_f32_e32 v63, 0xba800000, v33
	v_mul_f32_e32 v33, v51, v51
	v_mul_f32_e32 v35, v53, v53
	v_mul_f32_e32 v66, v55, v55
	v_mul_f32_e32 v67, v57, v57
	v_mul_f32_e32 v68, v59, v59
	v_mul_f32_e32 v69, v61, v61
	v_fmac_f32_e32 v33, v50, v50
	v_fmac_f32_e32 v35, v52, v52
	v_fmac_f32_e32 v66, v54, v54
	v_fmac_f32_e32 v67, v56, v56
	v_mul_f32_e32 v70, v63, v63
	v_mul_f32_e32 v71, v65, v65
	v_fmac_f32_e32 v68, v58, v58
	v_fmac_f32_e32 v69, v60, v60
	v_add_f32_e32 v33, v33, v35
	v_add_f32_e32 v35, v66, v67
	v_fmac_f32_e32 v70, v62, v62
	v_fmac_f32_e32 v71, v64, v64
	v_add_f32_e32 v66, v68, v69
	v_add_f32_e32 v33, v33, v35
	v_add_f32_e32 v67, v70, v71
	v_add_f32_e32 v33, v66, v33
	v_add_f32_e32 v33, v67, v33
	s_nop 1
	v_add_f32_dpp v33, v33, v33 quad_perm:[1,0,3,2] row_mask:0xf bank_mask:0xf bound_ctrl:1
	s_nop 1
	v_add_f32_dpp v33, v33, v33 quad_perm:[2,3,0,1] row_mask:0xf bank_mask:0xf bound_ctrl:1
	s_nop 1
	v_add_f32_dpp v33, v33, v33 row_half_mirror row_mask:0xf bank_mask:0xf bound_ctrl:1
	s_nop 1
	v_add_f32_dpp v33, v33, v33 row_mirror row_mask:0xf bank_mask:0xf bound_ctrl:1
	v_mov_b32_e32 v35, v33
	s_nop 1
	v_permlane16_swap_b32_e32 v33, v35
	v_add_f32_e32 v33, v33, v35
	v_mov_b32_e32 v35, v33
	s_nop 1
	v_permlane32_swap_b32_e32 v33, v35
	v_add_f32_e32 v33, v33, v35
	v_fmamk_f32 v33, v33, 0x3a800000, v198
	v_mul_f32_e32 v35, 0x4b800000, v33
	v_cmp_gt_f32_e32 vcc, s25, v33
	s_nop 1
	v_cndmask_b32_e32 v33, v33, v35, vcc
	v_rsq_f32_e32 v33, v33
	s_nop 0
	v_mul_f32_e32 v35, 0x45800000, v33
	v_cndmask_b32_e32 v66, v33, v35, vcc
	v_pk_mul_f32 v[52:53], v[52:53], v[66:67] op_sel_hi:[1,0]
	v_pk_mul_f32 v[50:51], v[50:51], v[66:67] op_sel_hi:[1,0]
	v_pk_mul_f32 v[54:55], v[54:55], v[66:67] op_sel_hi:[1,0]
	v_pk_mul_f32 v[56:57], v[56:57], v[66:67] op_sel_hi:[1,0]
	v_pk_mul_f32 v[58:59], v[58:59], v[66:67] op_sel_hi:[1,0]
	v_pk_mul_f32 v[60:61], v[60:61], v[66:67] op_sel_hi:[1,0]
	v_pk_mul_f32 v[62:63], v[62:63], v[66:67] op_sel_hi:[1,0]
	v_pk_mul_f32 v[64:65], v[64:65], v[66:67] op_sel_hi:[1,0]
	v_pk_fma_f32 v[8:9], v[108:109], v[50:51], v[124:125]
	v_pk_fma_f32 v[10:11], v[110:111], v[52:53], v[126:127]
	v_pk_fma_f32 v[18:19], v[102:103], v[56:57], v[118:119]
	v_pk_fma_f32 v[16:17], v[100:101], v[54:55], v[116:117]
	v_pk_fma_f32 v[14:15], v[114:115], v[60:61], v[130:131]
	v_pk_fma_f32 v[12:13], v[112:113], v[58:59], v[128:129]
	v_pk_fma_f32 v[22:23], v[106:107], v[64:65], v[122:123]
	v_pk_fma_f32 v[20:21], v[104:105], v[62:63], v[120:121]
	v_cvt_pk_f16_f32 v1, v10, v11
	v_cvt_pk_f16_f32 v0, v8, v9
	v_cvt_pk_f16_f32 v3, v18, v19
	v_cvt_pk_f16_f32 v2, v16, v17
	v_cvt_pk_f16_f32 v5, v14, v15
	v_cvt_pk_f16_f32 v4, v12, v13
	v_cvt_pk_f16_f32 v7, v22, v23
	v_cvt_pk_f16_f32 v6, v20, v21
	global_store_dwordx2 v[48:49], v[0:1], off nt
	global_store_dwordx2 v[48:49], v[2:3], off offset:512 nt
	global_store_dwordx2 v[48:49], v[4:5], off offset:1024 nt
	global_store_dwordx2 v[48:49], v[6:7], off offset:1536 nt
	flat_load_dwordx4 v[0:3], v[90:91]
	s_nop 0
	flat_load_dwordx4 v[4:7], v[46:47]
	v_lshl_add_u64 v[24:25], v[46:47], 0, s[26:27]
	v_cmp_lt_i32_e32 vcc, s20, v32
	s_or_b64 s[4:5], vcc, s[4:5]
	s_waitcnt vmcnt(0) lgkmcnt(0)
; DI unsigned pk_bf16(float lo, float hi) { unsigned r; asm("v_cvt_pk_bf16_f32 %0, %1, %2" : "=v"(r) : "v"(lo), "v"(hi)); return r; }
; DI void phase_row(const Params& P, const void* xs, int sh, void* xd, int dh, int ln, int gl, int gidx, float wgt, int modl, int shidx, bool dry = false) {
;     ...
;         if (modl >= 0) {
;             const float* shp = mod + (modl * 2 + b) * 9216 + shidx * 1024; const float* sc = shp + 1024;
; #pragma unroll
;             for (int j = 0; j < 4; ++j) { const f32x4 s4 = *(const f32x4*)(shp + 4 * lane + 256 * j), c4 = *(const f32x4*)(sc + 4 * lane + 256 * j);
;                 const f32x4 u = v[j] * (c4 + 1.f) + s4; u32x2 o; o.x = pk_bf16(u[0], u[1]); o.y = pk_bf16(u[2], u[3]);
;                 *(u32x2*)(U + (size_t)row * D + 4 * lane + 256 * j) = o; }
;         }
	v_pk_add_f32 v[0:1], v[0:1], 1.0 op_sel_hi:[1,0]
	v_pk_add_f32 v[2:3], v[2:3], 1.0 op_sel_hi:[1,0]
	v_pk_fma_f32 v[0:1], v[8:9], v[0:1], v[4:5]
	v_pk_fma_f32 v[2:3], v[10:11], v[2:3], v[6:7]
	v_cvt_pk_bf16_f32 v0, v0, v1
	s_nop 0
	v_cvt_pk_bf16_f32 v1, v2, v3
	flat_store_dwordx2 v[44:45], v[0:1]
	flat_load_dwordx4 v[0:3], v[24:25] offset:1024
	s_nop 0
	flat_load_dwordx4 v[4:7], v[46:47] offset:1024
	s_waitcnt vmcnt(0) lgkmcnt(0)
	v_pk_add_f32 v[0:1], v[0:1], 1.0 op_sel_hi:[1,0]
	v_pk_add_f32 v[2:3], v[2:3], 1.0 op_sel_hi:[1,0]
	v_pk_fma_f32 v[0:1], v[16:17], v[0:1], v[4:5]
	v_pk_fma_f32 v[2:3], v[18:19], v[2:3], v[6:7]
	v_cvt_pk_bf16_f32 v0, v0, v1
	s_nop 0
	v_cvt_pk_bf16_f32 v1, v2, v3
	flat_store_dwordx2 v[44:45], v[0:1] offset:512
	flat_load_dwordx4 v[0:3], v[24:25] offset:2048
	s_nop 0
	flat_load_dwordx4 v[4:7], v[46:47] offset:2048
	s_waitcnt vmcnt(0) lgkmcnt(0)
	v_pk_add_f32 v[0:1], v[0:1], 1.0 op_sel_hi:[1,0]
	v_pk_add_f32 v[2:3], v[2:3], 1.0 op_sel_hi:[1,0]
	v_pk_fma_f32 v[0:1], v[12:13], v[0:1], v[4:5]
	v_pk_fma_f32 v[2:3], v[14:15], v[2:3], v[6:7]
	v_cvt_pk_bf16_f32 v0, v0, v1
	s_nop 0
	v_cvt_pk_bf16_f32 v1, v2, v3
	flat_store_dwordx2 v[44:45], v[0:1] offset:1024
	flat_load_dwordx4 v[0:3], v[24:25] offset:3072
	s_nop 0
	flat_load_dwordx4 v[4:7], v[46:47] offset:3072
	s_waitcnt vmcnt(0) lgkmcnt(0)
	v_pk_add_f32 v[0:1], v[0:1], 1.0 op_sel_hi:[1,0]
	v_pk_add_f32 v[2:3], v[2:3], 1.0 op_sel_hi:[1,0]
	v_pk_fma_f32 v[0:1], v[20:21], v[0:1], v[4:5]
	v_pk_fma_f32 v[2:3], v[22:23], v[2:3], v[6:7]
	v_cvt_pk_bf16_f32 v0, v0, v1
	s_nop 0
	v_cvt_pk_bf16_f32 v1, v2, v3
	flat_store_dwordx2 v[44:45], v[0:1] offset:1536
	s_andn2_b64 exec, exec, s[4:5]
	s_cbranch_execnz .LBB0_233
